# C11: +MFMA issue reorder/no setprio in GEMM loop, gmlp epilogue single wait, attention/retd keep output stores in flight, EpiRes gate loads batched
# baseline (speedup 1.0000x reference)
.LBB0_101:
	v_readfirstlane_b32 s2, v140
	s_ashr_i32 s3, s2, 7
	s_and_b32 s22, s58, 1
	s_lshr_b32 s2, s2, 1
	s_lshl_b32 s10, s22, 6
	s_and_b32 s2, s2, 32
	s_or_b32 s26, s2, s10
	s_ashr_i32 s2, s58, 2
	s_bfe_u32 s28, s58, 0x10001
	s_lshl_b32 s10, s28, 2
	s_lshl_b32 s29, s2, 7
	s_add_i32 s74, s3, s10
	v_or_b32_e32 v0, s29, v145
	v_or_b32_e32 v152, s26, v0
	s_lshl_b32 s10, s74, 6
	s_ashr_i32 s11, s10, 31
	v_mov_b64_e32 v[2:3], s[72:73]
	v_or_b32_e32 v150, 16, v152
	v_mad_i64_i32 v[4:5], s[20:21], v152, s64, v[2:3]
	s_lshl_b64 s[82:83], s[10:11], 1
	v_mad_i64_i32 v[2:3], s[10:11], v150, s64, v[2:3]
	v_lshl_add_u64 v[4:5], v[4:5], 0, s[82:83]
	v_lshlrev_b32_e32 v0, 1, v146
	v_lshl_add_u64 v[2:3], v[2:3], 0, s[82:83]
	s_waitcnt vmcnt(10)
	v_lshl_add_u64 v[6:7], v[4:5], 0, v[0:1]
	s_waitcnt vmcnt(8)
	v_lshl_add_u64 v[14:15], v[2:3], 0, v[0:1]
	global_load_dwordx4 v[2:5], v[6:7], off offset:2048
	s_nop 0
	global_load_dwordx4 v[6:9], v[6:7], off offset:2112
	s_nop 0
	global_load_dwordx4 v[10:13], v[14:15], off offset:2048
	s_nop 0
	global_load_dwordx4 v[14:17], v[14:15], off offset:2112
	s_and_b32 s40, s2, 0x7f
	s_cmp_eq_u32 s40, 0
	s_cselect_b64 s[10:11], -1, 0
	s_add_i32 s3, s2, 0xffffff00
	s_ashr_i32 s16, s58, 9
	s_lshr_b32 s20, s3, 1
	s_cmpk_lt_i32 s2, 0x100
	s_cselect_b64 s[78:79], -1, 0
	v_cndmask_b32_e64 v0, 0, 1, s[10:11]
	s_and_b64 s[2:3], s[78:79], exec
	s_cselect_b32 s2, s16, s20
	v_readfirstlane_b32 s21, v0
	s_cselect_b32 s20, s21, 3
	s_lshl_b32 s23, s2, 8
	s_addk_i32 s23, 0x7e80
	v_ashrrev_i32_e32 v153, 31, v152
	v_ashrrev_i32_e32 v151, 31, v150
	s_cmp_lt_i32 s20, 1
	s_cbranch_scc1 .LBB0_106
	s_cmp_lg_u32 s20, 1
	s_mov_b64 s[2:3], -1
	s_cbranch_scc0 .LBB0_104
	s_lshl_b32 s2, s20, 7
	s_add_i32 s16, s23, s2
	s_mov_b64 s[2:3], 0

.LBB0_257:
	v_readfirstlane_b32 s22, v140
	s_ashr_i32 s10, s22, 7
	s_ashr_i32 s11, s10, 31
	s_lshl_b64 s[20:21], s[10:11], 15
	v_and_or_b32 v80, s22, 64, v145
	v_lshl_add_u64 v[18:19], v[74:75], 0, s[20:21]
	v_lshlrev_b32_e32 v0, 8, v80
	s_waitcnt vmcnt(2)
	v_or_b32_e32 v22, 0x1000, v0
	v_mov_b32_e32 v23, v1
	s_waitcnt vmcnt(0)
	v_lshl_add_u64 v[14:15], v[18:19], 0, s[34:35]
	v_lshl_add_u64 v[2:3], v[18:19], 0, v[22:23]
	v_or_b32_e32 v26, 0x2000, v0
	v_mov_b32_e32 v27, v1
	v_lshl_add_u64 v[6:7], v[14:15], 0, v[22:23]
	v_lshl_add_u64 v[20:21], v[18:19], 0, v[0:1]
	global_load_dwordx4 v[54:57], v[2:3], off
	v_or_b32_e32 v0, 0x3000, v0
	global_load_dwordx4 v[6:9], v[6:7], off
	v_lshl_add_u64 v[2:3], v[18:19], 0, v[26:27]
	v_lshl_add_u64 v[10:11], v[14:15], 0, v[26:27]
	s_mov_b64 s[20:21], 0xc0
	v_mov_b64_e32 v[82:83], s[72:73]
	global_load_dwordx4 v[58:61], v[2:3], off
	v_lshl_add_u64 v[14:15], v[14:15], 0, v[0:1]
	global_load_dwordx4 v[10:13], v[10:11], off
	v_lshl_add_u64 v[2:3], v[18:19], 0, v[0:1]
	v_lshl_add_u64 v[30:31], v[18:19], 0, s[20:21]
	v_mad_i64_i32 v[66:67], s[20:21], v87, s64, v[82:83]
	global_load_dwordx4 v[62:65], v[2:3], off
	v_lshl_add_u64 v[66:67], v[76:77], 1, v[66:67]
	global_load_dwordx4 v[14:17], v[14:15], off
	v_lshl_add_u64 v[2:3], v[18:19], 0, 64
	s_mov_b64 s[20:21], 0x1000
	v_lshl_add_u64 v[4:5], v[2:3], 0, v[22:23]
	v_lshl_add_u64 v[96:97], v[66:67], 0, s[20:21]
	v_add_co_u32_e32 v66, vcc, s26, v66
	global_load_dwordx4 v[50:53], v[20:21], off
	global_load_dwordx4 v[38:41], v[4:5], off
	v_lshl_add_u64 v[4:5], v[2:3], 0, v[26:27]
	v_lshl_add_u64 v[2:3], v[2:3], 0, v[0:1]
	v_lshl_add_u64 v[22:23], v[30:31], 0, v[22:23]
	v_lshl_add_u64 v[26:27], v[30:31], 0, v[26:27]
	v_lshl_add_u64 v[30:31], v[30:31], 0, v[0:1]
	v_addc_co_u32_e32 v67, vcc, 0, v67, vcc
	global_load_dwordx4 v[34:37], v[20:21], off offset:64
	global_load_dwordx4 v[42:45], v[4:5], off
	global_load_dwordx4 v[46:49], v[2:3], off
	s_mul_i32 s11, s10, 0x4800
	global_load_dwordx4 v[2:5], v[20:21], off offset:128
	s_add_i32 s16, s16, s96
	global_load_dwordx4 v[18:21], v[20:21], off offset:192
	v_add_u32_e32 v87, s23, v87
	global_load_dwordx4 v[22:25], v[22:23], off
	s_nop 0
	global_load_dwordx4 v[26:29], v[26:27], off
	s_nop 0
	global_load_dwordx4 v[30:33], v[30:31], off
	s_nop 0
	global_load_dwordx4 v[66:69], v[66:67], off
	s_nop 0
	global_load_dwordx4 v[70:73], v[96:97], off offset:48
	global_load_dwordx4 v[88:91], v[96:97], off offset:32
	global_load_dwordx4 v[92:95], v[96:97], off offset:16
	s_waitcnt vmcnt(3)
	v_lshlrev_b32_e32 v150, 16, v66
	v_and_b32_e32 v149, 0xffff0000, v66
	v_lshlrev_b32_e32 v148, 16, v67
	v_and_b32_e32 v146, 0xffff0000, v67
	v_lshlrev_b32_e32 v137, 16, v68
	v_and_b32_e32 v136, 0xffff0000, v68
	v_lshlrev_b32_e32 v135, 16, v69
	v_and_b32_e32 v134, 0xffff0000, v69
	s_waitcnt vmcnt(0)
	v_lshlrev_b32_e32 v133, 16, v92
	v_and_b32_e32 v132, 0xffff0000, v92
	v_lshlrev_b32_e32 v131, 16, v93
	v_and_b32_e32 v130, 0xffff0000, v93
	v_lshlrev_b32_e32 v129, 16, v94
	v_and_b32_e32 v128, 0xffff0000, v94
	v_lshlrev_b32_e32 v127, 16, v95
	v_and_b32_e32 v126, 0xffff0000, v95
	v_lshlrev_b32_e32 v125, 16, v88
	v_and_b32_e32 v124, 0xffff0000, v88
	v_lshlrev_b32_e32 v123, 16, v89
	v_and_b32_e32 v122, 0xffff0000, v89
	v_lshlrev_b32_e32 v121, 16, v90
	v_and_b32_e32 v120, 0xffff0000, v90
	v_lshlrev_b32_e32 v119, 16, v91
	v_and_b32_e32 v118, 0xffff0000, v91
	v_lshlrev_b32_e32 v117, 16, v70
	v_and_b32_e32 v116, 0xffff0000, v70
	v_lshlrev_b32_e32 v115, 16, v71
	v_and_b32_e32 v114, 0xffff0000, v71
	v_lshlrev_b32_e32 v113, 16, v72
	v_and_b32_e32 v112, 0xffff0000, v72
	v_lshlrev_b32_e32 v111, 16, v73
	v_and_b32_e32 v110, 0xffff0000, v73
	global_load_dwordx4 v[66:69], v[96:97], off offset:112
	global_load_dwordx4 v[70:73], v[96:97], off offset:96
	global_load_dwordx4 v[88:91], v[96:97], off offset:80
	global_load_dwordx4 v[92:95], v[96:97], off offset:64
	s_waitcnt vmcnt(3)
	v_and_b32_e32 v0, 0xffff0000, v66
	s_waitcnt vmcnt(2)
	v_lshlrev_b32_e32 v81, 16, v73
	s_waitcnt vmcnt(1)
	v_lshlrev_b32_e32 v101, 16, v88
	v_and_b32_e32 v100, 0xffff0000, v88
	v_lshlrev_b32_e32 v99, 16, v89
	v_and_b32_e32 v98, 0xffff0000, v89
	v_lshlrev_b32_e32 v89, 16, v72
	v_and_b32_e32 v88, 0xffff0000, v72
	v_lshlrev_b32_e32 v72, 16, v66
	v_add_f32_e32 v66, 0, v150
	v_add_f32_e32 v66, v66, v149
	v_add_f32_e32 v66, v66, v148
	v_add_f32_e32 v66, v66, v146
	v_add_f32_e32 v66, v66, v137
	v_add_f32_e32 v66, v66, v136
	v_add_f32_e32 v66, v66, v135
	v_add_f32_e32 v66, v66, v134
	v_add_f32_e32 v66, v66, v133
	v_add_f32_e32 v66, v66, v132
	v_add_f32_e32 v66, v66, v131
	v_add_f32_e32 v66, v66, v130
	v_add_f32_e32 v66, v66, v129
	v_add_f32_e32 v66, v66, v128
	v_add_f32_e32 v66, v66, v127
	v_add_f32_e32 v66, v66, v126
	v_add_f32_e32 v66, v66, v125
	v_add_f32_e32 v66, v66, v124
	v_add_f32_e32 v66, v66, v123
	v_add_f32_e32 v66, v66, v122
	v_add_f32_e32 v66, v66, v121
	v_add_f32_e32 v66, v66, v120
	v_add_f32_e32 v66, v66, v119
	v_add_f32_e32 v66, v66, v118
	v_add_f32_e32 v66, v66, v117
	v_add_f32_e32 v66, v66, v116
	v_add_f32_e32 v66, v66, v115
	v_add_f32_e32 v66, v66, v114
	v_add_f32_e32 v66, v66, v113
	v_add_f32_e32 v66, v66, v112
	v_add_f32_e32 v66, v66, v111
	s_waitcnt vmcnt(0)
	v_lshlrev_b32_e32 v109, 16, v92
	v_add_f32_e32 v66, v66, v110
	v_and_b32_e32 v108, 0xffff0000, v92
	v_add_f32_e32 v66, v66, v109
	v_lshlrev_b32_e32 v107, 16, v93
	v_add_f32_e32 v66, v66, v108
	v_and_b32_e32 v106, 0xffff0000, v93
	v_add_f32_e32 v66, v66, v107
	v_lshlrev_b32_e32 v105, 16, v94
	v_add_f32_e32 v66, v66, v106
	v_and_b32_e32 v104, 0xffff0000, v94
	v_add_f32_e32 v66, v66, v105
	v_lshlrev_b32_e32 v103, 16, v95
	v_add_f32_e32 v66, v66, v104
	v_and_b32_e32 v102, 0xffff0000, v95
	v_add_f32_e32 v66, v66, v103
	v_add_f32_e32 v66, v66, v102
	v_add_f32_e32 v66, v66, v101
	v_add_f32_e32 v66, v66, v100
	v_add_f32_e32 v66, v66, v99
	v_lshlrev_b32_e32 v97, 16, v90
	v_add_f32_e32 v66, v66, v98
	v_and_b32_e32 v96, 0xffff0000, v90
	v_add_f32_e32 v66, v66, v97
	v_lshlrev_b32_e32 v95, 16, v91
	v_add_f32_e32 v66, v66, v96
	v_and_b32_e32 v94, 0xffff0000, v91
	v_add_f32_e32 v66, v66, v95
	v_lshlrev_b32_e32 v93, 16, v70
	v_add_f32_e32 v66, v66, v94
	v_and_b32_e32 v92, 0xffff0000, v70
	v_add_f32_e32 v66, v66, v93
	v_lshlrev_b32_e32 v91, 16, v71
	v_add_f32_e32 v66, v66, v92
	v_and_b32_e32 v90, 0xffff0000, v71
	v_add_f32_e32 v66, v66, v91
	v_add_f32_e32 v66, v66, v90
	v_add_f32_e32 v66, v66, v89
	v_add_f32_e32 v66, v66, v88
	v_and_b32_e32 v73, 0xffff0000, v73
	v_add_f32_e32 v66, v66, v81
	v_add_f32_e32 v66, v66, v73
	v_add_f32_e32 v66, v66, v72
	v_add_f32_e32 v70, v66, v0
	v_and_b32_e32 v66, 0xffff0000, v67
	v_lshlrev_b32_e32 v67, 16, v67
	v_and_b32_e32 v156, 0xffff0000, v68
	v_lshlrev_b32_e32 v157, 16, v68
	v_add_f32_e32 v68, v70, v67
	v_add_f32_e32 v68, v68, v66
	v_add_f32_e32 v68, v68, v157
	v_lshlrev_b32_e32 v153, 16, v69
	v_add_f32_e32 v68, v68, v156
	v_and_b32_e32 v152, 0xffff0000, v69
	v_add_f32_e32 v68, v68, v153
	v_add_f32_e32 v68, v68, v152
	v_fmac_f32_e32 v149, 0xbc800000, v68
	v_fmac_f32_e32 v150, 0xbc800000, v68
	v_mul_f32_e32 v69, v149, v149
	v_fmac_f32_e32 v69, v150, v150
	v_fmac_f32_e32 v148, 0xbc800000, v68
	v_fmac_f32_e32 v69, v148, v148
	v_fmac_f32_e32 v146, 0xbc800000, v68
	v_fmac_f32_e32 v69, v146, v146
	v_fmac_f32_e32 v137, 0xbc800000, v68
	v_fmac_f32_e32 v69, v137, v137
	v_fmac_f32_e32 v136, 0xbc800000, v68
	v_fmac_f32_e32 v69, v136, v136
	v_fmac_f32_e32 v135, 0xbc800000, v68
	v_fmac_f32_e32 v69, v135, v135
	v_fmac_f32_e32 v134, 0xbc800000, v68
	v_fmac_f32_e32 v69, v134, v134
	v_fmac_f32_e32 v133, 0xbc800000, v68
	v_fmac_f32_e32 v69, v133, v133
	v_fmac_f32_e32 v132, 0xbc800000, v68
	v_fmac_f32_e32 v69, v132, v132
	v_fmac_f32_e32 v131, 0xbc800000, v68
	v_fmac_f32_e32 v69, v131, v131
	v_fmac_f32_e32 v130, 0xbc800000, v68
	v_fmac_f32_e32 v69, v130, v130
	v_fmac_f32_e32 v129, 0xbc800000, v68
	v_fmac_f32_e32 v69, v129, v129
	v_fmac_f32_e32 v128, 0xbc800000, v68
	v_fmac_f32_e32 v69, v128, v128
	v_fmac_f32_e32 v127, 0xbc800000, v68
	v_fmac_f32_e32 v69, v127, v127
	v_fmac_f32_e32 v126, 0xbc800000, v68
	v_fmac_f32_e32 v69, v126, v126
	v_fmac_f32_e32 v125, 0xbc800000, v68
	v_fmac_f32_e32 v69, v125, v125
	v_fmac_f32_e32 v124, 0xbc800000, v68
	v_fmac_f32_e32 v69, v124, v124
	v_fmac_f32_e32 v123, 0xbc800000, v68
	v_fmac_f32_e32 v69, v123, v123
	v_fmac_f32_e32 v122, 0xbc800000, v68
	v_fmac_f32_e32 v69, v122, v122
	v_fmac_f32_e32 v121, 0xbc800000, v68
	v_fmac_f32_e32 v69, v121, v121
	v_fmac_f32_e32 v120, 0xbc800000, v68
	v_fmac_f32_e32 v69, v120, v120
	v_fmac_f32_e32 v119, 0xbc800000, v68
	v_fmac_f32_e32 v69, v119, v119
	v_fmac_f32_e32 v118, 0xbc800000, v68
	v_fmac_f32_e32 v69, v118, v118
	v_fmac_f32_e32 v117, 0xbc800000, v68
	v_fmac_f32_e32 v69, v117, v117
	v_fmac_f32_e32 v116, 0xbc800000, v68
	v_fmac_f32_e32 v69, v116, v116
	v_fmac_f32_e32 v115, 0xbc800000, v68
	v_fmac_f32_e32 v69, v115, v115
	v_fmac_f32_e32 v114, 0xbc800000, v68
	v_fmac_f32_e32 v69, v114, v114
	v_fmac_f32_e32 v113, 0xbc800000, v68
	v_fmac_f32_e32 v69, v113, v113
	v_fmac_f32_e32 v112, 0xbc800000, v68
	v_fmac_f32_e32 v69, v112, v112
	v_fmac_f32_e32 v111, 0xbc800000, v68
	v_fmac_f32_e32 v69, v111, v111
	v_fmac_f32_e32 v110, 0xbc800000, v68
	v_fmac_f32_e32 v69, v110, v110
	v_fmac_f32_e32 v109, 0xbc800000, v68
	v_fmac_f32_e32 v69, v109, v109
	v_fmac_f32_e32 v108, 0xbc800000, v68
	v_fmac_f32_e32 v69, v108, v108
	v_fmac_f32_e32 v107, 0xbc800000, v68
	v_fmac_f32_e32 v69, v107, v107
	v_fmac_f32_e32 v106, 0xbc800000, v68
	v_fmac_f32_e32 v69, v106, v106
	v_fmac_f32_e32 v105, 0xbc800000, v68
	v_fmac_f32_e32 v69, v105, v105
	v_fmac_f32_e32 v104, 0xbc800000, v68
	v_fmac_f32_e32 v69, v104, v104
	v_fmac_f32_e32 v103, 0xbc800000, v68
	v_fmac_f32_e32 v69, v103, v103
	v_fmac_f32_e32 v102, 0xbc800000, v68
	v_fmac_f32_e32 v69, v102, v102
	v_fmac_f32_e32 v101, 0xbc800000, v68
	v_fmac_f32_e32 v69, v101, v101
	v_fmac_f32_e32 v100, 0xbc800000, v68
	v_fmac_f32_e32 v69, v100, v100
	v_fmac_f32_e32 v99, 0xbc800000, v68
	v_fmac_f32_e32 v69, v99, v99
	v_fmac_f32_e32 v98, 0xbc800000, v68
	v_fmac_f32_e32 v69, v98, v98
	v_fmac_f32_e32 v97, 0xbc800000, v68
	v_fmac_f32_e32 v69, v97, v97
	v_fmac_f32_e32 v96, 0xbc800000, v68
	v_fmac_f32_e32 v69, v96, v96
	v_fmac_f32_e32 v95, 0xbc800000, v68
	v_fmac_f32_e32 v69, v95, v95
	v_fmac_f32_e32 v94, 0xbc800000, v68
	v_fmac_f32_e32 v69, v94, v94
	v_fmac_f32_e32 v93, 0xbc800000, v68
	v_fmac_f32_e32 v69, v93, v93
	v_fmac_f32_e32 v92, 0xbc800000, v68
	v_fmac_f32_e32 v69, v92, v92
	v_fmac_f32_e32 v91, 0xbc800000, v68
	v_fmac_f32_e32 v69, v91, v91
	v_fmac_f32_e32 v90, 0xbc800000, v68
	v_fmac_f32_e32 v69, v90, v90
	v_fmac_f32_e32 v89, 0xbc800000, v68
	v_fmac_f32_e32 v69, v89, v89
	v_fmac_f32_e32 v88, 0xbc800000, v68
	v_fmac_f32_e32 v69, v88, v88
	v_fmac_f32_e32 v81, 0xbc800000, v68
	v_fmac_f32_e32 v69, v81, v81
	v_fmac_f32_e32 v73, 0xbc800000, v68
	v_mul_f32_e32 v158, 0x3c800000, v68
	v_fmac_f32_e32 v69, v73, v73
	v_fmac_f32_e32 v72, 0xbc800000, v68
	v_fmac_f32_e32 v69, v72, v72
	v_fmac_f32_e32 v0, 0xbc800000, v68
	v_pk_add_f32 v[70:71], v[66:67], v[158:159] op_sel_hi:[1,0] neg_lo:[0,1] neg_hi:[0,1]
	v_fmac_f32_e32 v69, v0, v0
	v_pk_mul_f32 v[66:67], v[70:71], v[70:71]
	s_nop 0
	v_add_f32_e32 v67, v67, v69
	v_pk_add_f32 v[68:69], v[156:157], v[158:159] op_sel_hi:[1,0] neg_lo:[0,1] neg_hi:[0,1]
	v_add_f32_e32 v151, v66, v67
	v_pk_mul_f32 v[66:67], v[68:69], v[68:69]
	s_nop 0
	v_add_f32_e32 v67, v67, v151
	v_add_f32_e32 v151, v66, v67
	v_pk_add_f32 v[66:67], v[152:153], v[158:159] op_sel_hi:[1,0] neg_lo:[0,1] neg_hi:[0,1]
	global_load_dwordx4 v[156:159], v[78:79], off offset:16
	global_load_dwordx4 v[160:163], v[78:79], off
	global_load_dwordx4 v[196:199], v[78:79], off offset:48
	global_load_dwordx4 v[200:203], v[78:79], off offset:32
	global_load_dwordx4 v[204:207], v[78:79], off offset:80
	global_load_dwordx4 v[208:211], v[78:79], off offset:64
	global_load_dwordx4 v[212:215], v[78:79], off offset:112
	global_load_dwordx4 v[216:219], v[78:79], off offset:96
	global_load_dwordx4 v[220:223], v[78:79], off offset:144
	global_load_dwordx4 v[224:227], v[78:79], off offset:128
	global_load_dwordx4 v[228:231], v[78:79], off offset:176
	global_load_dwordx4 v[232:235], v[78:79], off offset:160
	global_load_dwordx4 v[236:239], v[78:79], off offset:208
	global_load_dwordx4 v[240:243], v[78:79], off offset:192
	global_load_dwordx4 v[244:247], v[78:79], off offset:240
	global_load_dwordx4 v[248:251], v[78:79], off offset:224
	v_pk_mul_f32 v[152:153], v[66:67], v[66:67]
	s_nop 0
	v_add_f32_e32 v151, v153, v151
	v_add_f32_e32 v151, v152, v151
	v_fmamk_f32 v151, v151, 0x3c800000, v177
	v_rsq_f32_e32 v151, v151
	s_nop 0
	v_mul_f32_e32 v150, v150, v151
	v_mul_f32_e32 v149, v149, v151
	v_mul_f32_e32 v148, v148, v151
	v_mul_f32_e32 v146, v146, v151
	v_mul_f32_e32 v137, v137, v151
	v_mul_f32_e32 v136, v136, v151
	v_mul_f32_e32 v135, v135, v151
	v_mul_f32_e32 v134, v134, v151
	v_mul_f32_e32 v133, v133, v151
	v_mul_f32_e32 v132, v132, v151
	v_mul_f32_e32 v131, v131, v151
	v_mul_f32_e32 v130, v130, v151
	v_mul_f32_e32 v129, v129, v151
	v_mul_f32_e32 v128, v128, v151
	v_mul_f32_e32 v127, v127, v151
	v_mul_f32_e32 v126, v126, v151
	v_mul_f32_e32 v125, v125, v151
	v_mul_f32_e32 v124, v124, v151
	v_mul_f32_e32 v123, v123, v151
	v_mul_f32_e32 v122, v122, v151
	v_mul_f32_e32 v121, v121, v151
	v_mul_f32_e32 v120, v120, v151
	v_mul_f32_e32 v119, v119, v151
	v_mul_f32_e32 v118, v118, v151
	v_mul_f32_e32 v117, v117, v151
	v_mul_f32_e32 v116, v116, v151
	v_mul_f32_e32 v115, v115, v151
	v_mul_f32_e32 v114, v114, v151
	v_mul_f32_e32 v113, v113, v151
	v_mul_f32_e32 v112, v112, v151
	v_mul_f32_e32 v111, v111, v151
	v_mul_f32_e32 v110, v110, v151
	v_mul_f32_e32 v109, v109, v151
	v_mul_f32_e32 v108, v108, v151
	v_mul_f32_e32 v107, v107, v151
	v_mul_f32_e32 v106, v106, v151
	v_mul_f32_e32 v105, v105, v151
	v_mul_f32_e32 v104, v104, v151
	v_mul_f32_e32 v103, v103, v151
	v_mul_f32_e32 v102, v102, v151
	v_mul_f32_e32 v101, v101, v151
	v_mul_f32_e32 v100, v100, v151
	v_mul_f32_e32 v99, v99, v151
	v_mul_f32_e32 v98, v98, v151
	v_mul_f32_e32 v97, v97, v151
	v_mul_f32_e32 v96, v96, v151
	v_mul_f32_e32 v95, v95, v151
	v_mul_f32_e32 v94, v94, v151
	v_mul_f32_e32 v93, v93, v151
	v_mul_f32_e32 v92, v92, v151
	v_mul_f32_e32 v91, v91, v151
	v_mul_f32_e32 v90, v90, v151
	v_mul_f32_e32 v89, v89, v151
	v_mul_f32_e32 v88, v88, v151
	v_mul_f32_e32 v81, v81, v151
	v_mul_f32_e32 v73, v73, v151
	v_mul_f32_e32 v0, v0, v151
	v_mul_f32_e32 v72, v72, v151
	v_mul_f32_e32 v70, v70, v151
	v_mul_f32_e32 v68, v68, v151
	v_mul_f32_e32 v66, v66, v151
	s_waitcnt vmcnt(15)
	v_mul_f32_e32 v137, v156, v137
	s_waitcnt vmcnt(14)
	v_mul_f32_e32 v150, v160, v150
	v_mul_f32_e32 v149, v161, v149
	v_cvt_pk_bf16_f32 v160, v150, v149
	v_mul_f32_e32 v148, v162, v148
	v_mul_f32_e32 v146, v163, v146
	v_cvt_pk_bf16_f32 v161, v148, v146
	v_mul_f32_e32 v136, v157, v136
	v_cvt_pk_bf16_f32 v162, v137, v136
	v_mul_f32_e32 v135, v158, v135
	v_mul_f32_e32 v134, v159, v134
	v_cvt_pk_bf16_f32 v163, v135, v134
	ds_write_b128 v86, v[160:163]
	s_waitcnt vmcnt(13)
	v_mul_f32_e32 v129, v196, v129
	s_waitcnt vmcnt(12)
	v_mul_f32_e32 v133, v200, v133
	v_mul_f32_e32 v132, v201, v132
	v_cvt_pk_bf16_f32 v132, v133, v132
	v_mul_f32_e32 v131, v202, v131
	v_mul_f32_e32 v130, v203, v130
	v_cvt_pk_bf16_f32 v133, v131, v130
	v_mul_f32_e32 v128, v197, v128
	v_cvt_pk_bf16_f32 v134, v129, v128
	v_mul_f32_e32 v127, v198, v127
	v_mul_f32_e32 v126, v199, v126
	v_cvt_pk_bf16_f32 v135, v127, v126
	ds_write_b128 v86, v[132:135] offset:16
	s_waitcnt vmcnt(11)
	v_mul_f32_e32 v121, v204, v121
	s_waitcnt vmcnt(10)
	v_mul_f32_e32 v125, v208, v125
	v_mul_f32_e32 v124, v209, v124
	v_cvt_pk_bf16_f32 v124, v125, v124
	v_mul_f32_e32 v123, v210, v123
	v_mul_f32_e32 v122, v211, v122
	v_cvt_pk_bf16_f32 v125, v123, v122
	v_mul_f32_e32 v120, v205, v120
	v_cvt_pk_bf16_f32 v126, v121, v120
	v_mul_f32_e32 v119, v206, v119
	v_mul_f32_e32 v118, v207, v118
	v_cvt_pk_bf16_f32 v127, v119, v118
	ds_write_b128 v86, v[124:127] offset:32
	s_waitcnt vmcnt(9)
	v_mul_f32_e32 v113, v212, v113
	s_waitcnt vmcnt(8)
	v_mul_f32_e32 v117, v216, v117
	v_mul_f32_e32 v116, v217, v116
	v_cvt_pk_bf16_f32 v116, v117, v116
	v_mul_f32_e32 v115, v218, v115
	v_mul_f32_e32 v114, v219, v114
	v_cvt_pk_bf16_f32 v117, v115, v114
	v_mul_f32_e32 v112, v213, v112
	v_cvt_pk_bf16_f32 v118, v113, v112
	v_mul_f32_e32 v111, v214, v111
	v_mul_f32_e32 v110, v215, v110
	v_cvt_pk_bf16_f32 v119, v111, v110
	ds_write_b128 v86, v[116:119] offset:48
	s_waitcnt vmcnt(7)
	v_mul_f32_e32 v105, v220, v105
	s_waitcnt vmcnt(6)
	v_mul_f32_e32 v109, v224, v109
	v_mul_f32_e32 v108, v225, v108
	v_cvt_pk_bf16_f32 v108, v109, v108
	v_mul_f32_e32 v107, v226, v107
	v_mul_f32_e32 v106, v227, v106
	v_cvt_pk_bf16_f32 v109, v107, v106
	v_mul_f32_e32 v104, v221, v104
	v_cvt_pk_bf16_f32 v110, v105, v104
	v_mul_f32_e32 v103, v222, v103
	v_mul_f32_e32 v102, v223, v102
	v_cvt_pk_bf16_f32 v111, v103, v102
	ds_write_b128 v86, v[108:111] offset:64
	s_waitcnt vmcnt(5)
	v_mul_f32_e32 v97, v228, v97
	s_waitcnt vmcnt(4)
	v_mul_f32_e32 v101, v232, v101
	v_mul_f32_e32 v100, v233, v100
	v_cvt_pk_bf16_f32 v100, v101, v100
	v_mul_f32_e32 v99, v234, v99
	v_mul_f32_e32 v98, v235, v98
	v_cvt_pk_bf16_f32 v101, v99, v98
	v_mul_f32_e32 v96, v229, v96
	v_cvt_pk_bf16_f32 v102, v97, v96
	v_mul_f32_e32 v95, v230, v95
	v_mul_f32_e32 v94, v231, v94
	v_cvt_pk_bf16_f32 v103, v95, v94
	ds_write_b128 v86, v[100:103] offset:80
	s_waitcnt vmcnt(3)
	v_mul_f32_e32 v89, v236, v89
	s_waitcnt vmcnt(2)
	v_mul_f32_e32 v93, v240, v93
	v_mul_f32_e32 v92, v241, v92
	v_cvt_pk_bf16_f32 v92, v93, v92
	v_mul_f32_e32 v91, v242, v91
	v_mul_f32_e32 v90, v243, v90
	v_cvt_pk_bf16_f32 v93, v91, v90
	v_mul_f32_e32 v88, v237, v88
	v_cvt_pk_bf16_f32 v94, v89, v88
	v_mul_f32_e32 v81, v238, v81
	v_mul_f32_e32 v73, v239, v73
	v_cvt_pk_bf16_f32 v95, v81, v73
	ds_write_b128 v86, v[92:95] offset:96
	v_mov_b32_e32 v81, v1
	s_waitcnt vmcnt(1)
	v_mul_f32_e32 v68, v245, v68
	s_waitcnt vmcnt(0)
	v_mul_f32_e32 v0, v249, v0
	v_mul_f32_e32 v72, v248, v72
	v_cvt_pk_bf16_f32 v92, v72, v0
	v_mul_f32_e32 v0, v71, v151
	v_mul_f32_e32 v0, v250, v0
	v_mul_f32_e32 v70, v251, v70
	v_cvt_pk_bf16_f32 v93, v0, v70
	v_mul_f32_e32 v0, v69, v151
	v_mul_f32_e32 v0, v244, v0
	v_cvt_pk_bf16_f32 v94, v0, v68
	v_mul_f32_e32 v0, v67, v151
	v_mul_f32_e32 v0, v246, v0
	v_mul_f32_e32 v66, v247, v66
	v_cvt_pk_bf16_f32 v95, v0, v66
	v_add_u32_e32 v0, s11, v84
	ds_write_b128 v86, v[92:95] offset:112
	s_waitcnt lgkmcnt(0)
	s_barrier
	ds_read_b64_tr_b16 v[68:69], v0 offset:576
	ds_read_b64_tr_b16 v[66:67], v0
	ds_read_b64_tr_b16 v[70:71], v0 offset:32
	ds_read_b64_tr_b16 v[72:73], v0 offset:608
	ds_read_b64_tr_b16 v[88:89], v0 offset:64
	ds_read_b64_tr_b16 v[90:91], v0 offset:640
	ds_read_b64_tr_b16 v[92:93], v0 offset:96
	ds_read_b64_tr_b16 v[94:95], v0 offset:672
	s_waitcnt lgkmcnt(6)
	v_mfma_f32_16x16x32_bf16 v[96:99], v[66:69], v[50:53], 0
	s_and_b32 s11, s22, 0xffffff80
	v_mfma_f32_16x16x32_bf16 v[100:103], v[66:69], v[54:57], 0
	v_mfma_f32_16x16x32_bf16 v[104:107], v[66:69], v[58:61], 0
	v_mfma_f32_16x16x32_bf16 v[66:69], v[66:69], v[62:65], 0
	s_waitcnt lgkmcnt(4)
	v_mfma_f32_16x16x32_bf16 v[108:111], v[70:73], v[50:53], 0
	v_mfma_f32_16x16x32_bf16 v[112:115], v[70:73], v[54:57], 0
	v_mfma_f32_16x16x32_bf16 v[116:119], v[70:73], v[58:61], 0
	v_mfma_f32_16x16x32_bf16 v[70:73], v[70:73], v[62:65], 0
	s_waitcnt lgkmcnt(2)
	v_mfma_f32_16x16x32_bf16 v[120:123], v[88:91], v[50:53], 0
	v_mfma_f32_16x16x32_bf16 v[124:127], v[88:91], v[54:57], 0
	v_mfma_f32_16x16x32_bf16 v[128:131], v[88:91], v[58:61], 0
	v_mfma_f32_16x16x32_bf16 v[88:91], v[88:91], v[62:65], 0
	s_waitcnt lgkmcnt(0)
	v_mfma_f32_16x16x32_bf16 v[50:53], v[92:95], v[50:53], 0
	v_mfma_f32_16x16x32_bf16 v[54:57], v[92:95], v[54:57], 0
	v_mfma_f32_16x16x32_bf16 v[58:61], v[92:95], v[58:61], 0
	v_mfma_f32_16x16x32_bf16 v[62:65], v[92:95], v[62:65], 0
	ds_read_b64_tr_b16 v[92:93], v0 offset:4608
	ds_read_b64_tr_b16 v[94:95], v0 offset:5184
	ds_read_b64_tr_b16 v[132:133], v0 offset:4640
	ds_read_b64_tr_b16 v[134:135], v0 offset:5216
	ds_read_b64_tr_b16 v[148:149], v0 offset:4672
	ds_read_b64_tr_b16 v[150:151], v0 offset:5248
	ds_read_b64_tr_b16 v[156:157], v0 offset:4704
	ds_read_b64_tr_b16 v[158:159], v0 offset:5280
	s_waitcnt lgkmcnt(6)
	v_mfma_f32_16x16x32_bf16 v[96:99], v[92:95], v[34:37], v[96:99]
	v_mfma_f32_16x16x32_bf16 v[100:103], v[92:95], v[38:41], v[100:103]
	v_mfma_f32_16x16x32_bf16 v[104:107], v[92:95], v[42:45], v[104:107]
	v_mfma_f32_16x16x32_bf16 v[66:69], v[92:95], v[46:49], v[66:69]
	s_waitcnt lgkmcnt(4)
	v_mfma_f32_16x16x32_bf16 v[92:95], v[132:135], v[34:37], v[108:111]
	v_mfma_f32_16x16x32_bf16 v[108:111], v[132:135], v[38:41], v[112:115]
	v_mfma_f32_16x16x32_bf16 v[112:115], v[132:135], v[42:45], v[116:119]
	v_mfma_f32_16x16x32_bf16 v[70:73], v[132:135], v[46:49], v[70:73]
	s_waitcnt lgkmcnt(2)
	v_mfma_f32_16x16x32_bf16 v[116:119], v[148:151], v[34:37], v[120:123]
	v_mfma_f32_16x16x32_bf16 v[120:123], v[148:151], v[38:41], v[124:127]
	v_mfma_f32_16x16x32_bf16 v[124:127], v[148:151], v[42:45], v[128:131]
	v_mfma_f32_16x16x32_bf16 v[88:91], v[148:151], v[46:49], v[88:91]
	s_waitcnt lgkmcnt(0)
	v_mfma_f32_16x16x32_bf16 v[34:37], v[156:159], v[34:37], v[50:53]
	v_mfma_f32_16x16x32_bf16 v[38:41], v[156:159], v[38:41], v[54:57]
	v_mfma_f32_16x16x32_bf16 v[42:45], v[156:159], v[42:45], v[58:61]
	v_mfma_f32_16x16x32_bf16 v[46:49], v[156:159], v[46:49], v[62:65]
	ds_read_b64_tr_b16 v[50:51], v0 offset:9216
	ds_read_b64_tr_b16 v[52:53], v0 offset:9792
	ds_read_b64_tr_b16 v[54:55], v0 offset:9248
	ds_read_b64_tr_b16 v[56:57], v0 offset:9824
	ds_read_b64_tr_b16 v[58:59], v0 offset:9280
	ds_read_b64_tr_b16 v[60:61], v0 offset:9856
	ds_read_b64_tr_b16 v[62:63], v0 offset:9312
	ds_read_b64_tr_b16 v[64:65], v0 offset:9888
	s_waitcnt lgkmcnt(6)
	v_mfma_f32_16x16x32_bf16 v[96:99], v[50:53], v[2:5], v[96:99]
	v_mfma_f32_16x16x32_bf16 v[100:103], v[50:53], v[6:9], v[100:103]
	v_mfma_f32_16x16x32_bf16 v[104:107], v[50:53], v[10:13], v[104:107]
	v_mfma_f32_16x16x32_bf16 v[50:53], v[50:53], v[14:17], v[66:69]
	s_waitcnt lgkmcnt(4)
	v_mfma_f32_16x16x32_bf16 v[66:69], v[54:57], v[2:5], v[92:95]
	v_mfma_f32_16x16x32_bf16 v[92:95], v[54:57], v[6:9], v[108:111]
	v_mfma_f32_16x16x32_bf16 v[108:111], v[54:57], v[10:13], v[112:115]
	s_waitcnt lgkmcnt(2)
	v_mfma_f32_16x16x32_bf16 v[116:119], v[58:61], v[2:5], v[116:119]
	v_mfma_f32_16x16x32_bf16 v[120:123], v[58:61], v[6:9], v[120:123]
	v_mfma_f32_16x16x32_bf16 v[124:127], v[58:61], v[10:13], v[124:127]
	v_mfma_f32_16x16x32_bf16 v[58:61], v[58:61], v[14:17], v[88:91]
	s_waitcnt lgkmcnt(0)
	v_mfma_f32_16x16x32_bf16 v[88:91], v[62:65], v[6:9], v[38:41]
	v_mfma_f32_16x16x32_bf16 v[128:131], v[62:65], v[10:13], v[42:45]
	ds_read_b64_tr_b16 v[6:7], v0 offset:13824
	ds_read_b64_tr_b16 v[8:9], v0 offset:14400
	ds_read_b64_tr_b16 v[10:11], v0 offset:13856
	ds_read_b64_tr_b16 v[12:13], v0 offset:14432
	ds_read_b64_tr_b16 v[148:149], v0 offset:13888
	ds_read_b64_tr_b16 v[150:151], v0 offset:14464
	ds_read_b64_tr_b16 v[156:157], v0 offset:13920
	ds_read_b64_tr_b16 v[158:159], v0 offset:14496
	v_mfma_f32_16x16x32_bf16 v[2:5], v[62:65], v[2:5], v[34:37]
	v_mfma_f32_16x16x32_bf16 v[112:115], v[54:57], v[14:17], v[70:73]
	v_mfma_f32_16x16x32_bf16 v[132:135], v[62:65], v[14:17], v[46:49]
	s_waitcnt lgkmcnt(6)
	v_mfma_f32_16x16x32_bf16 v[70:73], v[6:9], v[18:21], v[96:99]
	v_mfma_f32_16x16x32_bf16 v[54:57], v[6:9], v[22:25], v[100:103]
	v_mfma_f32_16x16x32_bf16 v[42:45], v[6:9], v[26:29], v[104:107]
	v_mfma_f32_16x16x32_bf16 v[14:17], v[6:9], v[30:33], v[50:53]
	s_waitcnt lgkmcnt(4)
	v_mfma_f32_16x16x32_bf16 v[66:69], v[10:13], v[18:21], v[66:69]
	v_mfma_f32_16x16x32_bf16 v[38:41], v[10:13], v[26:29], v[108:111]
	s_waitcnt lgkmcnt(2)
	v_mfma_f32_16x16x32_bf16 v[62:65], v[148:151], v[18:21], v[116:119]
	v_mfma_f32_16x16x32_bf16 v[34:37], v[148:151], v[26:29], v[124:127]
	v_mfma_f32_16x16x32_bf16 v[6:9], v[148:151], v[30:33], v[58:61]
	s_waitcnt lgkmcnt(0)
	v_mfma_f32_16x16x32_bf16 v[58:61], v[156:159], v[18:21], v[2:5]
	v_mfma_f32_16x16x32_bf16 v[18:21], v[156:159], v[26:29], v[128:131]
	v_or_b32_e32 v28, s11, v80
	v_ashrrev_i32_e32 v29, 31, v28
	v_lshl_or_b32 v26, s10, 6, v144
	v_mfma_f32_16x16x32_bf16 v[50:53], v[10:13], v[22:25], v[92:95]
	v_ashrrev_i32_e32 v27, 31, v26
	v_lshlrev_b64 v[26:27], 1, v[26:27]
	s_ashr_i32 s10, s11, 31
	v_mfma_f32_16x16x32_bf16 v[10:13], v[10:13], v[30:33], v[112:115]
	v_mfma_f32_16x16x32_bf16 v[2:5], v[156:159], v[30:33], v[132:135]
	v_mov_b32_e32 v29, s10
	v_lshl_add_u64 v[28:29], v[28:29], 2, s[50:51]
	v_mfma_f32_16x16x32_bf16 v[46:49], v[148:151], v[22:25], v[120:123]
	v_mfma_f32_16x16x32_bf16 v[22:25], v[156:159], v[22:25], v[88:91]
	v_mov_b32_e32 v195, 0
	v_lshl_add_u64 v[196:197], s[52:53], 0, v[80:81]
	v_mad_u64_u32 v[200:201], s[20:21], v196, s64, v[82:83]
	v_mov_b32_e32 v198, v201
	v_mad_u64_u32 v[198:199], s[20:21], v197, s64, v[198:199]
	v_mov_b32_e32 v201, v198
	v_lshl_add_u64 v[200:201], v[200:201], 0, v[26:27]
	v_lshlrev_b64 v[196:197], 11, v[196:197]
	v_lshl_add_u64 v[208:209], s[70:71], 0, v[196:197]
	v_lshl_add_u64 v[208:209], v[208:209], 0, v[26:27]
	global_load_dword v216, v[28:29], off
	global_load_dwordx2 v[220:221], v[200:201], off offset:3584
	global_load_dwordx2 v[222:223], v[200:201], off offset:3616
	global_load_dwordx2 v[224:225], v[200:201], off offset:3648
	global_load_dwordx2 v[226:227], v[200:201], off offset:3680
	v_or_b32_e32 v194, 16, v80
	v_lshl_add_u64 v[196:197], s[52:53], 0, v[194:195]
	v_mad_u64_u32 v[202:203], s[20:21], v196, s64, v[82:83]
	v_mov_b32_e32 v198, v203
	v_mad_u64_u32 v[198:199], s[20:21], v197, s64, v[198:199]
	v_mov_b32_e32 v203, v198
	v_lshl_add_u64 v[202:203], v[202:203], 0, v[26:27]
	v_lshlrev_b64 v[196:197], 11, v[196:197]
	v_lshl_add_u64 v[210:211], s[70:71], 0, v[196:197]
	v_lshl_add_u64 v[210:211], v[210:211], 0, v[26:27]
	global_load_dword v217, v[28:29], off offset:64
	global_load_dwordx2 v[228:229], v[202:203], off offset:3584
	global_load_dwordx2 v[230:231], v[202:203], off offset:3616
	global_load_dwordx2 v[232:233], v[202:203], off offset:3648
	global_load_dwordx2 v[234:235], v[202:203], off offset:3680
	v_or_b32_e32 v194, 32, v80
	v_lshl_add_u64 v[196:197], s[52:53], 0, v[194:195]
	v_mad_u64_u32 v[204:205], s[20:21], v196, s64, v[82:83]
	v_mov_b32_e32 v198, v205
	v_mad_u64_u32 v[198:199], s[20:21], v197, s64, v[198:199]
	v_mov_b32_e32 v205, v198
	v_lshl_add_u64 v[204:205], v[204:205], 0, v[26:27]
	v_lshlrev_b64 v[196:197], 11, v[196:197]
	v_lshl_add_u64 v[212:213], s[70:71], 0, v[196:197]
	v_lshl_add_u64 v[212:213], v[212:213], 0, v[26:27]
	global_load_dword v218, v[28:29], off offset:128
	global_load_dwordx2 v[236:237], v[204:205], off offset:3584
	global_load_dwordx2 v[238:239], v[204:205], off offset:3616
	global_load_dwordx2 v[240:241], v[204:205], off offset:3648
	global_load_dwordx2 v[242:243], v[204:205], off offset:3680
	v_or_b32_e32 v194, 48, v80
	v_lshl_add_u64 v[196:197], s[52:53], 0, v[194:195]
	v_mad_u64_u32 v[206:207], s[20:21], v196, s64, v[82:83]
	v_mov_b32_e32 v198, v207
	v_mad_u64_u32 v[198:199], s[20:21], v197, s64, v[198:199]
	v_mov_b32_e32 v207, v198
	v_lshl_add_u64 v[206:207], v[206:207], 0, v[26:27]
	v_lshlrev_b64 v[196:197], 11, v[196:197]
	v_lshl_add_u64 v[214:215], s[70:71], 0, v[196:197]
	v_lshl_add_u64 v[214:215], v[214:215], 0, v[26:27]
	global_load_dword v219, v[28:29], off offset:192
	global_load_dwordx2 v[244:245], v[206:207], off offset:3584
	global_load_dwordx2 v[246:247], v[206:207], off offset:3616
	global_load_dwordx2 v[248:249], v[206:207], off offset:3648
	global_load_dwordx2 v[250:251], v[206:207], off offset:3680
	s_add_u32 s52, s52, s24
	s_addc_u32 s53, s53, s25
	s_waitcnt vmcnt(0)
	v_add_f32_e32 v70, v70, v216
	v_add_f32_e32 v71, v71, v216
	v_add_f32_e32 v72, v72, v216
	v_add_f32_e32 v73, v73, v216
	v_lshlrev_b32_e32 v194, 16, v220
	v_and_b32_e32 v195, 0xffff0000, v220
	v_lshlrev_b32_e32 v196, 16, v221
	v_and_b32_e32 v197, 0xffff0000, v221
	v_pk_mul_f32 v[70:71], v[70:71], v[194:195]
	v_pk_mul_f32 v[72:73], v[72:73], v[196:197]
	v_cvt_pk_bf16_f32 v70, v70, v71
	v_cvt_pk_bf16_f32 v71, v72, v73
	global_store_dwordx2 v[208:209], v[70:71], off offset:1536
	v_add_f32_e32 v66, v66, v216
	v_add_f32_e32 v67, v67, v216
	v_add_f32_e32 v68, v68, v216
	v_add_f32_e32 v69, v69, v216
	v_lshlrev_b32_e32 v194, 16, v222
	v_and_b32_e32 v195, 0xffff0000, v222
	v_lshlrev_b32_e32 v196, 16, v223
	v_and_b32_e32 v197, 0xffff0000, v223
	v_pk_mul_f32 v[66:67], v[66:67], v[194:195]
	v_pk_mul_f32 v[68:69], v[68:69], v[196:197]
	v_cvt_pk_bf16_f32 v66, v66, v67
	v_cvt_pk_bf16_f32 v67, v68, v69
	global_store_dwordx2 v[208:209], v[66:67], off offset:1568
	v_add_f32_e32 v62, v62, v216
	v_add_f32_e32 v63, v63, v216
	v_add_f32_e32 v64, v64, v216
	v_add_f32_e32 v65, v65, v216
	v_lshlrev_b32_e32 v194, 16, v224
	v_and_b32_e32 v195, 0xffff0000, v224
	v_lshlrev_b32_e32 v196, 16, v225
	v_and_b32_e32 v197, 0xffff0000, v225
	v_pk_mul_f32 v[62:63], v[62:63], v[194:195]
	v_pk_mul_f32 v[64:65], v[64:65], v[196:197]
	v_cvt_pk_bf16_f32 v62, v62, v63
	v_cvt_pk_bf16_f32 v63, v64, v65
	global_store_dwordx2 v[208:209], v[62:63], off offset:1600
	v_add_f32_e32 v58, v58, v216
	v_add_f32_e32 v59, v59, v216
	v_add_f32_e32 v60, v60, v216
	v_add_f32_e32 v61, v61, v216
	v_lshlrev_b32_e32 v194, 16, v226
	v_and_b32_e32 v195, 0xffff0000, v226
	v_lshlrev_b32_e32 v196, 16, v227
	v_and_b32_e32 v197, 0xffff0000, v227
	v_pk_mul_f32 v[58:59], v[58:59], v[194:195]
	v_pk_mul_f32 v[60:61], v[60:61], v[196:197]
	v_cvt_pk_bf16_f32 v58, v58, v59
	v_cvt_pk_bf16_f32 v59, v60, v61
	global_store_dwordx2 v[208:209], v[58:59], off offset:1632
	s_nop 0
	v_add_f32_e32 v54, v54, v217
	v_add_f32_e32 v55, v55, v217
	v_add_f32_e32 v56, v56, v217
	v_add_f32_e32 v57, v57, v217
	v_lshlrev_b32_e32 v194, 16, v228
	v_and_b32_e32 v195, 0xffff0000, v228
	v_lshlrev_b32_e32 v196, 16, v229
	v_and_b32_e32 v197, 0xffff0000, v229
	v_pk_mul_f32 v[54:55], v[54:55], v[194:195]
	v_pk_mul_f32 v[56:57], v[56:57], v[196:197]
	v_cvt_pk_bf16_f32 v54, v54, v55
	v_cvt_pk_bf16_f32 v55, v56, v57
	global_store_dwordx2 v[210:211], v[54:55], off offset:1536
	v_add_f32_e32 v50, v50, v217
	v_add_f32_e32 v51, v51, v217
	v_add_f32_e32 v52, v52, v217
	v_add_f32_e32 v53, v53, v217
	v_lshlrev_b32_e32 v194, 16, v230
	v_and_b32_e32 v195, 0xffff0000, v230
	v_lshlrev_b32_e32 v196, 16, v231
	v_and_b32_e32 v197, 0xffff0000, v231
	v_pk_mul_f32 v[50:51], v[50:51], v[194:195]
	v_pk_mul_f32 v[52:53], v[52:53], v[196:197]
	v_cvt_pk_bf16_f32 v50, v50, v51
	v_cvt_pk_bf16_f32 v51, v52, v53
	global_store_dwordx2 v[210:211], v[50:51], off offset:1568
	v_add_f32_e32 v46, v46, v217
	v_add_f32_e32 v47, v47, v217
	v_add_f32_e32 v48, v48, v217
	v_add_f32_e32 v49, v49, v217
	v_lshlrev_b32_e32 v194, 16, v232
	v_and_b32_e32 v195, 0xffff0000, v232
	v_lshlrev_b32_e32 v196, 16, v233
	v_and_b32_e32 v197, 0xffff0000, v233
	v_pk_mul_f32 v[46:47], v[46:47], v[194:195]
	v_pk_mul_f32 v[48:49], v[48:49], v[196:197]
	v_cvt_pk_bf16_f32 v46, v46, v47
	v_cvt_pk_bf16_f32 v47, v48, v49
	global_store_dwordx2 v[210:211], v[46:47], off offset:1600
	v_add_f32_e32 v22, v22, v217
	v_add_f32_e32 v23, v23, v217
	v_add_f32_e32 v24, v24, v217
	v_add_f32_e32 v25, v25, v217
	v_lshlrev_b32_e32 v194, 16, v234
	v_and_b32_e32 v195, 0xffff0000, v234
	v_lshlrev_b32_e32 v196, 16, v235
	v_and_b32_e32 v197, 0xffff0000, v235
	v_pk_mul_f32 v[22:23], v[22:23], v[194:195]
	v_pk_mul_f32 v[24:25], v[24:25], v[196:197]
	v_cvt_pk_bf16_f32 v22, v22, v23
	v_cvt_pk_bf16_f32 v23, v24, v25
	global_store_dwordx2 v[210:211], v[22:23], off offset:1632
	s_nop 0
	v_add_f32_e32 v42, v42, v218
	v_add_f32_e32 v43, v43, v218
	v_add_f32_e32 v44, v44, v218
	v_add_f32_e32 v45, v45, v218
	v_lshlrev_b32_e32 v194, 16, v236
	v_and_b32_e32 v195, 0xffff0000, v236
	v_lshlrev_b32_e32 v196, 16, v237
	v_and_b32_e32 v197, 0xffff0000, v237
	v_pk_mul_f32 v[42:43], v[42:43], v[194:195]
	v_pk_mul_f32 v[44:45], v[44:45], v[196:197]
	v_cvt_pk_bf16_f32 v42, v42, v43
	v_cvt_pk_bf16_f32 v43, v44, v45
	global_store_dwordx2 v[212:213], v[42:43], off offset:1536
	v_add_f32_e32 v38, v38, v218
	v_add_f32_e32 v39, v39, v218
	v_add_f32_e32 v40, v40, v218
	v_add_f32_e32 v41, v41, v218
	v_lshlrev_b32_e32 v194, 16, v238
	v_and_b32_e32 v195, 0xffff0000, v238
	v_lshlrev_b32_e32 v196, 16, v239
	v_and_b32_e32 v197, 0xffff0000, v239
	v_pk_mul_f32 v[38:39], v[38:39], v[194:195]
	v_pk_mul_f32 v[40:41], v[40:41], v[196:197]
	v_cvt_pk_bf16_f32 v38, v38, v39
	v_cvt_pk_bf16_f32 v39, v40, v41
	global_store_dwordx2 v[212:213], v[38:39], off offset:1568
	v_add_f32_e32 v34, v34, v218
	v_add_f32_e32 v35, v35, v218
	v_add_f32_e32 v36, v36, v218
	v_add_f32_e32 v37, v37, v218
	v_lshlrev_b32_e32 v194, 16, v240
	v_and_b32_e32 v195, 0xffff0000, v240
	v_lshlrev_b32_e32 v196, 16, v241
	v_and_b32_e32 v197, 0xffff0000, v241
	v_pk_mul_f32 v[34:35], v[34:35], v[194:195]
	v_pk_mul_f32 v[36:37], v[36:37], v[196:197]
	v_cvt_pk_bf16_f32 v34, v34, v35
	v_cvt_pk_bf16_f32 v35, v36, v37
	global_store_dwordx2 v[212:213], v[34:35], off offset:1600
	v_add_f32_e32 v18, v18, v218
	v_add_f32_e32 v19, v19, v218
	v_add_f32_e32 v20, v20, v218
	v_add_f32_e32 v21, v21, v218
	v_lshlrev_b32_e32 v194, 16, v242
	v_and_b32_e32 v195, 0xffff0000, v242
	v_lshlrev_b32_e32 v196, 16, v243
	v_and_b32_e32 v197, 0xffff0000, v243
	v_pk_mul_f32 v[18:19], v[18:19], v[194:195]
	v_pk_mul_f32 v[20:21], v[20:21], v[196:197]
	v_cvt_pk_bf16_f32 v18, v18, v19
	v_cvt_pk_bf16_f32 v19, v20, v21
	global_store_dwordx2 v[212:213], v[18:19], off offset:1632
	s_nop 0
	v_add_f32_e32 v14, v14, v219
	v_add_f32_e32 v15, v15, v219
	v_add_f32_e32 v16, v16, v219
	v_add_f32_e32 v17, v17, v219
	v_lshlrev_b32_e32 v194, 16, v244
	v_and_b32_e32 v195, 0xffff0000, v244
	v_lshlrev_b32_e32 v196, 16, v245
	v_and_b32_e32 v197, 0xffff0000, v245
	v_pk_mul_f32 v[14:15], v[14:15], v[194:195]
	v_pk_mul_f32 v[16:17], v[16:17], v[196:197]
	v_cvt_pk_bf16_f32 v14, v14, v15
	v_cvt_pk_bf16_f32 v15, v16, v17
	global_store_dwordx2 v[214:215], v[14:15], off offset:1536
	v_add_f32_e32 v10, v10, v219
	v_add_f32_e32 v11, v11, v219
	v_add_f32_e32 v12, v12, v219
	v_add_f32_e32 v13, v13, v219
	v_lshlrev_b32_e32 v194, 16, v246
	v_and_b32_e32 v195, 0xffff0000, v246
	v_lshlrev_b32_e32 v196, 16, v247
	v_and_b32_e32 v197, 0xffff0000, v247
	v_pk_mul_f32 v[10:11], v[10:11], v[194:195]
	v_pk_mul_f32 v[12:13], v[12:13], v[196:197]
	v_cvt_pk_bf16_f32 v10, v10, v11
	v_cvt_pk_bf16_f32 v11, v12, v13
	global_store_dwordx2 v[214:215], v[10:11], off offset:1568
	v_add_f32_e32 v6, v6, v219
	v_add_f32_e32 v7, v7, v219
	v_add_f32_e32 v8, v8, v219
	v_add_f32_e32 v9, v9, v219
	v_lshlrev_b32_e32 v194, 16, v248
	v_and_b32_e32 v195, 0xffff0000, v248
	v_lshlrev_b32_e32 v196, 16, v249
	v_and_b32_e32 v197, 0xffff0000, v249
	v_pk_mul_f32 v[6:7], v[6:7], v[194:195]
	v_pk_mul_f32 v[8:9], v[8:9], v[196:197]
	v_cvt_pk_bf16_f32 v6, v6, v7
	v_cvt_pk_bf16_f32 v7, v8, v9
	global_store_dwordx2 v[214:215], v[6:7], off offset:1600
	v_add_f32_e32 v2, v2, v219
	v_add_f32_e32 v3, v3, v219
	v_add_f32_e32 v4, v4, v219
	v_add_f32_e32 v5, v5, v219
	v_lshlrev_b32_e32 v194, 16, v250
	v_and_b32_e32 v195, 0xffff0000, v250
	v_lshlrev_b32_e32 v196, 16, v251
	v_and_b32_e32 v197, 0xffff0000, v251
	v_pk_mul_f32 v[2:3], v[2:3], v[194:195]
	v_pk_mul_f32 v[4:5], v[4:5], v[196:197]
	v_cvt_pk_bf16_f32 v2, v2, v3
	v_cvt_pk_bf16_f32 v3, v4, v5
	global_store_dwordx2 v[214:215], v[2:3], off offset:1632
	s_cmp_ge_i32 s16, s2
	s_barrier
	s_cbranch_scc0 .LBB0_257
	s_branch .LBB0_254

.LBB0_260:
	s_andn2_b64 vcc, exec, s[10:11]
	v_readfirstlane_b32 s16, v140
	s_cbranch_vccnz .LBB0_259
	global_load_dwordx4 v[2:5], v[30:31], off offset:528
	global_load_dwordx4 v[6:9], v[30:31], off offset:512
	global_load_dwordx4 v[10:13], v[30:31], off offset:1040
	global_load_dwordx4 v[14:17], v[30:31], off offset:1024
	s_bfe_u32 s22, s16, 0x10006
	s_ashr_i32 s16, s16, 7
	v_lshl_or_b32 v18, s16, 10, v38
	v_ashrrev_i32_e32 v19, 31, v18
	s_mul_i32 s40, s22, 0x4800
	s_lshl_b32 s41, s16, 5
	v_lshl_add_u64 v[34:35], v[18:19], 2, v[32:33]
	s_add_i32 s22, s20, s22
	s_mov_b32 s42, s28
	s_mov_b32 s43, s21
	s_mov_b32 s44, s15
	s_and_b32 s98, s44, 3
	s_lshl_b32 s98, s98, 2
	v_mov_b32_e32 v200, s98
	global_load_dword v201, v200, s[2:3]
	global_load_dword v200, v200, s[2:3] offset:16
	s_mov_b32 s98, 1
	s_branch .LBB0_263

.LBB0_263:
	s_and_b32 s16, s44, 3
	s_lshl_b32 s16, s16, 2
	s_cmp_eq_u32 s98, 0
	s_cbranch_scc1 .Lmy_rd_n
	s_waitcnt vmcnt(0)
	s_mov_b32 s98, 0
	s_branch .Lmy_rd_j
.Lmy_rd_n:
	s_waitcnt vmcnt(16)
.Lmy_rd_j:
	v_mov_b32_e32 v19, v201
	v_mov_b32_e32 v18, v200
	v_and_b32_e32 v20, 0xffff0000, v6
	v_lshlrev_b32_e32 v23, 16, v2
	v_and_b32_e32 v27, 0xffff0000, v2
	v_lshlrev_b32_e32 v21, 16, v7
	v_and_b32_e32 v24, 0xffff0000, v7
	v_lshlrev_b32_e32 v41, 16, v3
	v_and_b32_e32 v42, 0xffff0000, v3
	v_lshlrev_b32_e32 v28, 16, v8
	v_and_b32_e32 v29, 0xffff0000, v8
	v_lshlrev_b32_e32 v46, 16, v4
	v_and_b32_e32 v47, 0xffff0000, v4
	v_lshlrev_b32_e32 v44, 16, v9
	v_and_b32_e32 v45, 0xffff0000, v9
	v_lshlrev_b32_e32 v48, 16, v5
	v_and_b32_e32 v49, 0xffff0000, v5
	s_add_i32 s44, s44, s96
	s_cmpk_gt_i32 s44, 0x40f
	s_cselect_b64 s[26:27], -1, 0
	s_and_b64 vcc, exec, s[26:27]
	s_nop 0
	v_mul_f32_e32 v19, v19, v36
	v_exp_f32_e32 v25, v19
	s_nop 0
	v_mul_f32_e32 v18, v18, v37
	v_exp_f32_e32 v43, v18
	v_lshlrev_b32_e32 v19, 16, v6
	v_mul_f32_e32 v18, v25, v19
	v_mul_f32_e32 v22, v25, v20
	v_cvt_pk_bf16_f32 v18, v18, v22
	v_mul_f32_e32 v22, v25, v23
	v_mul_f32_e32 v26, v25, v27
	v_mul_f32_e32 v19, v43, v19
	v_mul_f32_e32 v20, v43, v20
	v_cvt_pk_bf16_f32 v22, v22, v26
	v_cvt_pk_bf16_f32 v26, v19, v20
	v_mul_f32_e32 v19, v43, v23
	v_mul_f32_e32 v20, v43, v27
	v_cvt_pk_bf16_f32 v40, v19, v20
	v_mul_f32_e32 v19, v25, v21
	v_mul_f32_e32 v20, v25, v24
	v_cvt_pk_bf16_f32 v19, v19, v20
	v_mul_f32_e32 v20, v25, v41
	v_mul_f32_e32 v23, v25, v42
	v_cvt_pk_bf16_f32 v23, v20, v23
	v_mul_f32_e32 v20, v43, v21
	v_mul_f32_e32 v21, v43, v24
	v_cvt_pk_bf16_f32 v27, v20, v21
	v_mul_f32_e32 v20, v43, v41
	v_mul_f32_e32 v21, v43, v42
	v_cvt_pk_bf16_f32 v41, v20, v21
	v_mul_f32_e32 v20, v25, v28
	v_mul_f32_e32 v21, v25, v29
	v_cvt_pk_bf16_f32 v20, v20, v21
	v_mul_f32_e32 v21, v25, v46
	v_mul_f32_e32 v24, v25, v47
	v_cvt_pk_bf16_f32 v24, v21, v24
	v_mul_f32_e32 v21, v43, v28
	v_mul_f32_e32 v28, v43, v29
	v_cvt_pk_bf16_f32 v28, v21, v28
	v_mul_f32_e32 v21, v43, v46
	v_mul_f32_e32 v29, v43, v47
	v_cvt_pk_bf16_f32 v42, v21, v29
	v_mul_f32_e32 v21, v25, v44
	v_mul_f32_e32 v29, v25, v45
	v_cvt_pk_bf16_f32 v21, v21, v29
	v_mul_f32_e32 v29, v25, v48
	v_mul_f32_e32 v25, v25, v49
	v_cvt_pk_bf16_f32 v25, v29, v25
	v_mul_f32_e32 v29, v43, v44
	v_mul_f32_e32 v44, v43, v45
	v_cvt_pk_bf16_f32 v29, v29, v44
	v_mul_f32_e32 v44, v43, v48
	v_mul_f32_e32 v43, v43, v49
	v_cvt_pk_bf16_f32 v43, v44, v43
	v_add_u32_e32 v44, v143, v141
	ds_write_b128 v44, v[18:21]
	ds_write_b128 v44, v[22:25] offset:16
	ds_write_b128 v44, v[26:29] offset:18432
	ds_write_b128 v44, v[40:43] offset:18448
	ds_write_b128 v44, v[14:17] offset:36864
	ds_write_b128 v44, v[10:13] offset:36880
	s_waitcnt lgkmcnt(0)
	s_barrier
	s_cbranch_vccnz .LBB0_262
	s_and_b32 s16, s43, 0xffffff80
	v_add_u32_e32 v4, s16, v139
	v_mov_b64_e32 v[2:3], s[72:73]
	s_and_b32 s16, s42, 0xc0
	v_mad_i64_i32 v[2:3], s[46:47], v4, s64, v[2:3]
	s_lshl_b32 s16, s16, 1
	v_lshl_add_u64 v[2:3], v[2:3], 0, s[16:17]
	v_lshl_add_u64 v[14:15], v[2:3], 0, v[0:1]
	global_load_dwordx4 v[2:5], v[14:15], off offset:528
	global_load_dwordx4 v[6:9], v[14:15], off offset:512
	global_load_dwordx4 v[10:13], v[14:15], off offset:1040
	s_nop 0
	global_load_dwordx4 v[14:17], v[14:15], off offset:1024
	s_and_b32 s99, s44, 3
	s_lshl_b32 s99, s99, 2
	v_mov_b32_e32 v200, s99
	global_load_dword v201, v200, s[2:3]
	global_load_dword v200, v200, s[2:3] offset:16
	s_branch .LBB0_262

.LBB0_294:
	s_add_i32 s22, s10, 2
	s_add_u32 s23, s2, 0x80
	s_addc_u32 s11, s3, 0
	s_add_i32 s41, 0, 0x10000
	s_cmp_eq_u32 s75, s10
	s_cselect_b32 s11, s83, s11
	s_cselect_b32 s10, s82, s23
	v_add_u32_e32 v0, s41, v153
	s_cselect_b32 s45, s95, s21
	s_cselect_b32 s44, s94, s20
	s_add_i32 s23, 0, 0x14000
	ds_read_b128 v[130:133], v0
	ds_read_b128 v[134:137], v0 offset:1024
	ds_read_b128 v[160:163], v0 offset:2048
	ds_read_b128 v[164:167], v0 offset:3072
	v_add_u32_e32 v0, s23, v153
	ds_read_b128 v[168:171], v0
	ds_read_b128 v[172:175], v0 offset:1024
	ds_read_b128 v[202:205], v0 offset:2048
	ds_read_b128 v[206:209], v0 offset:3072
	s_add_i32 m0, s29, 0xc000
	ds_read_b128 v[210:213], v201
	ds_read_b128 v[214:217], v201 offset:1024
	ds_read_b128 v[218:221], v201 offset:2048
	ds_read_b128 v[222:225], v201 offset:3072
	ds_read_b128 v[226:229], v201 offset:4096
	ds_read_b128 v[230:233], v201 offset:5120
	ds_read_b128 v[234:237], v201 offset:6144
	ds_read_b128 v[238:241], v201 offset:7168
	global_load_lds_dwordx4 v156, s[2:3]
	s_add_i32 m0, s29, 0xe000
	s_nop 0
	global_load_lds_dwordx4 v158, s[2:3]
	s_waitcnt vmcnt(8)
	s_waitcnt lgkmcnt(0)
	s_barrier
	s_waitcnt lgkmcnt(0)
	v_mfma_f32_16x16x32_bf16 v[126:129], v[130:133], v[210:213], v[126:129]
	v_mfma_f32_16x16x32_bf16 v[122:125], v[160:163], v[210:213], v[122:125]
	v_mfma_f32_16x16x32_bf16 v[110:113], v[130:133], v[218:221], v[110:113]
	v_mfma_f32_16x16x32_bf16 v[106:109], v[160:163], v[218:221], v[106:109]
	v_mfma_f32_16x16x32_bf16 v[94:97], v[130:133], v[226:229], v[94:97]
	v_mfma_f32_16x16x32_bf16 v[90:93], v[160:163], v[226:229], v[90:93]
	v_mfma_f32_16x16x32_bf16 v[78:81], v[130:133], v[234:237], v[78:81]
	v_mfma_f32_16x16x32_bf16 v[74:77], v[160:163], v[234:237], v[74:77]
	v_mfma_f32_16x16x32_bf16 v[118:121], v[168:171], v[210:213], v[118:121]
	v_mfma_f32_16x16x32_bf16 v[114:117], v[202:205], v[210:213], v[114:117]
	v_mfma_f32_16x16x32_bf16 v[102:105], v[168:171], v[218:221], v[102:105]
	v_mfma_f32_16x16x32_bf16 v[98:101], v[202:205], v[218:221], v[98:101]
	v_mfma_f32_16x16x32_bf16 v[86:89], v[168:171], v[226:229], v[86:89]
	v_mfma_f32_16x16x32_bf16 v[82:85], v[202:205], v[226:229], v[82:85]
	v_mfma_f32_16x16x32_bf16 v[70:73], v[168:171], v[234:237], v[70:73]
	v_mfma_f32_16x16x32_bf16 v[66:69], v[202:205], v[234:237], v[66:69]
	v_mfma_f32_16x16x32_bf16 v[126:129], v[134:137], v[214:217], v[126:129]
	v_mfma_f32_16x16x32_bf16 v[122:125], v[164:167], v[214:217], v[122:125]
	v_mfma_f32_16x16x32_bf16 v[110:113], v[134:137], v[222:225], v[110:113]
	v_mfma_f32_16x16x32_bf16 v[106:109], v[164:167], v[222:225], v[106:109]
	v_mfma_f32_16x16x32_bf16 v[94:97], v[134:137], v[230:233], v[94:97]
	v_mfma_f32_16x16x32_bf16 v[90:93], v[164:167], v[230:233], v[90:93]
	v_mfma_f32_16x16x32_bf16 v[78:81], v[134:137], v[238:241], v[78:81]
	v_mfma_f32_16x16x32_bf16 v[74:77], v[164:167], v[238:241], v[74:77]
	v_mfma_f32_16x16x32_bf16 v[118:121], v[172:175], v[214:217], v[118:121]
	v_mfma_f32_16x16x32_bf16 v[114:117], v[206:209], v[214:217], v[114:117]
	v_mfma_f32_16x16x32_bf16 v[102:105], v[172:175], v[222:225], v[102:105]
	v_mfma_f32_16x16x32_bf16 v[98:101], v[206:209], v[222:225], v[98:101]
	v_mfma_f32_16x16x32_bf16 v[86:89], v[172:175], v[230:233], v[86:89]
	v_mfma_f32_16x16x32_bf16 v[82:85], v[206:209], v[230:233], v[82:85]
	v_mfma_f32_16x16x32_bf16 v[70:73], v[172:175], v[238:241], v[70:73]
	v_mfma_f32_16x16x32_bf16 v[66:69], v[206:209], v[238:241], v[66:69]
	s_barrier
	s_add_i32 s41, s41, s79
	s_mov_b32 m0, s41
	ds_read_b128 v[210:213], v201 offset:16384
	ds_read_b128 v[214:217], v201 offset:17408
	ds_read_b128 v[218:221], v201 offset:18432
	ds_read_b128 v[222:225], v201 offset:19456
	ds_read_b128 v[226:229], v201 offset:20480
	ds_read_b128 v[230:233], v201 offset:21504
	ds_read_b128 v[234:237], v201 offset:22528
	ds_read_b128 v[238:241], v201 offset:23552
	global_load_lds_dwordx4 v146, s[44:45]
	s_add_i32 m0, s41, 0x2000
	s_add_u32 s98, s44, 0x80
	s_addc_u32 s99, s45, 0
	global_load_lds_dwordx4 v150, s[44:45]
	s_add_u32 s44, s44, s76
	s_addc_u32 s45, s45, 0
	s_add_i32 s23, s23, s79
	s_mov_b32 m0, s23
	s_add_u32 s100, s10, 0x80
	s_addc_u32 s101, s11, 0
	global_load_lds_dwordx4 v146, s[44:45]
	s_add_i32 m0, s23, 0x2000
	s_nop 0
	global_load_lds_dwordx4 v150, s[44:45]
	s_mov_b32 m0, s29
	s_nop 0
	global_load_lds_dwordx4 v144, s[10:11]
	s_mov_b32 m0, s93
	s_nop 0
	global_load_lds_dwordx4 v148, s[10:11]
	s_waitcnt vmcnt(8)
	s_waitcnt lgkmcnt(0)
	s_barrier
	s_waitcnt lgkmcnt(0)
	v_mfma_f32_16x16x32_bf16 v[62:65], v[130:133], v[210:213], v[62:65]
	v_mfma_f32_16x16x32_bf16 v[58:61], v[160:163], v[210:213], v[58:61]
	v_mfma_f32_16x16x32_bf16 v[46:49], v[130:133], v[218:221], v[46:49]
	v_mfma_f32_16x16x32_bf16 v[42:45], v[160:163], v[218:221], v[42:45]
	v_mfma_f32_16x16x32_bf16 v[30:33], v[130:133], v[226:229], v[30:33]
	v_mfma_f32_16x16x32_bf16 v[26:29], v[160:163], v[226:229], v[26:29]
	v_mfma_f32_16x16x32_bf16 v[14:17], v[130:133], v[234:237], v[14:17]
	v_mfma_f32_16x16x32_bf16 v[10:13], v[160:163], v[234:237], v[10:13]
	v_mfma_f32_16x16x32_bf16 v[54:57], v[168:171], v[210:213], v[54:57]
	v_mfma_f32_16x16x32_bf16 v[50:53], v[202:205], v[210:213], v[50:53]
	v_mfma_f32_16x16x32_bf16 v[38:41], v[168:171], v[218:221], v[38:41]
	v_mfma_f32_16x16x32_bf16 v[34:37], v[202:205], v[218:221], v[34:37]
	v_mfma_f32_16x16x32_bf16 v[22:25], v[168:171], v[226:229], v[22:25]
	v_mfma_f32_16x16x32_bf16 v[18:21], v[202:205], v[226:229], v[18:21]
	v_mfma_f32_16x16x32_bf16 v[6:9], v[168:171], v[234:237], v[6:9]
	v_mfma_f32_16x16x32_bf16 v[2:5], v[202:205], v[234:237], v[2:5]
	v_mfma_f32_16x16x32_bf16 v[62:65], v[134:137], v[214:217], v[62:65]
	v_mfma_f32_16x16x32_bf16 v[58:61], v[164:167], v[214:217], v[58:61]
	v_mfma_f32_16x16x32_bf16 v[46:49], v[134:137], v[222:225], v[46:49]
	v_mfma_f32_16x16x32_bf16 v[42:45], v[164:167], v[222:225], v[42:45]
	v_mfma_f32_16x16x32_bf16 v[30:33], v[134:137], v[230:233], v[30:33]
	v_mfma_f32_16x16x32_bf16 v[26:29], v[164:167], v[230:233], v[26:29]
	v_mfma_f32_16x16x32_bf16 v[14:17], v[134:137], v[238:241], v[14:17]
	v_mfma_f32_16x16x32_bf16 v[10:13], v[164:167], v[238:241], v[10:13]
	v_mfma_f32_16x16x32_bf16 v[54:57], v[172:175], v[214:217], v[54:57]
	v_mfma_f32_16x16x32_bf16 v[50:53], v[206:209], v[214:217], v[50:53]
	v_mfma_f32_16x16x32_bf16 v[38:41], v[172:175], v[222:225], v[38:41]
	v_mfma_f32_16x16x32_bf16 v[34:37], v[206:209], v[222:225], v[34:37]
	v_mfma_f32_16x16x32_bf16 v[22:25], v[172:175], v[230:233], v[22:25]
	v_mfma_f32_16x16x32_bf16 v[18:21], v[206:209], v[230:233], v[18:21]
	v_mfma_f32_16x16x32_bf16 v[6:9], v[172:175], v[238:241], v[6:9]
	v_mfma_f32_16x16x32_bf16 v[2:5], v[206:209], v[238:241], v[2:5]
	s_barrier
	s_add_i32 s23, 0, 0x18000
	v_add_u32_e32 v0, s23, v153
	s_add_i32 s41, 0, 0x1c000
	ds_read_b128 v[130:133], v0
	ds_read_b128 v[134:137], v0 offset:1024
	ds_read_b128 v[160:163], v0 offset:2048
	ds_read_b128 v[164:167], v0 offset:3072
	v_add_u32_e32 v0, s41, v153
	ds_read_b128 v[168:171], v0
	ds_read_b128 v[172:175], v0 offset:1024
	ds_read_b128 v[202:205], v0 offset:2048
	ds_read_b128 v[206:209], v0 offset:3072
	s_add_u32 s10, s10, s76
	s_addc_u32 s11, s11, 0
	s_mov_b32 m0, s52
	ds_read_b128 v[210:213], v201 offset:32768
	ds_read_b128 v[214:217], v201 offset:33792
	ds_read_b128 v[218:221], v201 offset:34816
	ds_read_b128 v[222:225], v201 offset:35840
	ds_read_b128 v[226:229], v201 offset:36864
	ds_read_b128 v[230:233], v201 offset:37888
	ds_read_b128 v[234:237], v201 offset:38912
	ds_read_b128 v[238:241], v201 offset:39936
	global_load_lds_dwordx4 v144, s[10:11]
	s_mov_b32 m0, s53
	s_nop 0
	global_load_lds_dwordx4 v148, s[10:11]
	s_waitcnt vmcnt(8)
	s_waitcnt lgkmcnt(0)
	s_barrier
	s_waitcnt lgkmcnt(0)
	v_mfma_f32_16x16x32_bf16 v[126:129], v[130:133], v[210:213], v[126:129]
	v_mfma_f32_16x16x32_bf16 v[122:125], v[160:163], v[210:213], v[122:125]
	v_mfma_f32_16x16x32_bf16 v[110:113], v[130:133], v[218:221], v[110:113]
	v_mfma_f32_16x16x32_bf16 v[106:109], v[160:163], v[218:221], v[106:109]
	v_mfma_f32_16x16x32_bf16 v[94:97], v[130:133], v[226:229], v[94:97]
	v_mfma_f32_16x16x32_bf16 v[90:93], v[160:163], v[226:229], v[90:93]
	v_mfma_f32_16x16x32_bf16 v[78:81], v[130:133], v[234:237], v[78:81]
	v_mfma_f32_16x16x32_bf16 v[74:77], v[160:163], v[234:237], v[74:77]
	v_mfma_f32_16x16x32_bf16 v[118:121], v[168:171], v[210:213], v[118:121]
	v_mfma_f32_16x16x32_bf16 v[114:117], v[202:205], v[210:213], v[114:117]
	v_mfma_f32_16x16x32_bf16 v[102:105], v[168:171], v[218:221], v[102:105]
	v_mfma_f32_16x16x32_bf16 v[98:101], v[202:205], v[218:221], v[98:101]
	v_mfma_f32_16x16x32_bf16 v[86:89], v[168:171], v[226:229], v[86:89]
	v_mfma_f32_16x16x32_bf16 v[82:85], v[202:205], v[226:229], v[82:85]
	v_mfma_f32_16x16x32_bf16 v[70:73], v[168:171], v[234:237], v[70:73]
	v_mfma_f32_16x16x32_bf16 v[66:69], v[202:205], v[234:237], v[66:69]
	v_mfma_f32_16x16x32_bf16 v[126:129], v[134:137], v[214:217], v[126:129]
	v_mfma_f32_16x16x32_bf16 v[122:125], v[164:167], v[214:217], v[122:125]
	v_mfma_f32_16x16x32_bf16 v[110:113], v[134:137], v[222:225], v[110:113]
	v_mfma_f32_16x16x32_bf16 v[106:109], v[164:167], v[222:225], v[106:109]
	v_mfma_f32_16x16x32_bf16 v[94:97], v[134:137], v[230:233], v[94:97]
	v_mfma_f32_16x16x32_bf16 v[90:93], v[164:167], v[230:233], v[90:93]
	v_mfma_f32_16x16x32_bf16 v[78:81], v[134:137], v[238:241], v[78:81]
	v_mfma_f32_16x16x32_bf16 v[74:77], v[164:167], v[238:241], v[74:77]
	v_mfma_f32_16x16x32_bf16 v[118:121], v[172:175], v[214:217], v[118:121]
	v_mfma_f32_16x16x32_bf16 v[114:117], v[206:209], v[214:217], v[114:117]
	v_mfma_f32_16x16x32_bf16 v[102:105], v[172:175], v[222:225], v[102:105]
	v_mfma_f32_16x16x32_bf16 v[98:101], v[206:209], v[222:225], v[98:101]
	v_mfma_f32_16x16x32_bf16 v[86:89], v[172:175], v[230:233], v[86:89]
	v_mfma_f32_16x16x32_bf16 v[82:85], v[206:209], v[230:233], v[82:85]
	v_mfma_f32_16x16x32_bf16 v[70:73], v[172:175], v[238:241], v[70:73]
	v_mfma_f32_16x16x32_bf16 v[66:69], v[206:209], v[238:241], v[66:69]
	s_barrier
	s_add_i32 s10, s23, s79
	s_mov_b32 m0, s10
	ds_read_b128 v[210:213], v201 offset:49152
	ds_read_b128 v[214:217], v201 offset:50176
	ds_read_b128 v[218:221], v201 offset:51200
	ds_read_b128 v[222:225], v201 offset:52224
	ds_read_b128 v[226:229], v201 offset:53248
	ds_read_b128 v[230:233], v201 offset:54272
	ds_read_b128 v[234:237], v201 offset:55296
	ds_read_b128 v[238:241], v201 offset:56320
	global_load_lds_dwordx4 v146, s[98:99]
	s_add_i32 m0, s10, 0x2000
	s_add_i32 s10, s41, s79
	global_load_lds_dwordx4 v150, s[98:99]
	s_add_u32 s98, s98, s76
	s_addc_u32 s99, s99, 0
	s_mov_b32 m0, s10
	s_nop 0
	global_load_lds_dwordx4 v146, s[98:99]
	s_add_i32 m0, s10, 0x2000
	s_nop 0
	global_load_lds_dwordx4 v150, s[98:99]
	s_mov_b32 m0, s26
	s_nop 0
	global_load_lds_dwordx4 v144, s[100:101]
	s_mov_b32 m0, s27
	s_nop 0
	global_load_lds_dwordx4 v148, s[100:101]
	s_waitcnt vmcnt(8)
	s_waitcnt lgkmcnt(0)
	s_barrier
	s_waitcnt lgkmcnt(0)
	v_mfma_f32_16x16x32_bf16 v[62:65], v[130:133], v[210:213], v[62:65]
	v_mfma_f32_16x16x32_bf16 v[58:61], v[160:163], v[210:213], v[58:61]
	v_mfma_f32_16x16x32_bf16 v[46:49], v[130:133], v[218:221], v[46:49]
	v_mfma_f32_16x16x32_bf16 v[42:45], v[160:163], v[218:221], v[42:45]
	v_mfma_f32_16x16x32_bf16 v[30:33], v[130:133], v[226:229], v[30:33]
	v_mfma_f32_16x16x32_bf16 v[26:29], v[160:163], v[226:229], v[26:29]
	v_mfma_f32_16x16x32_bf16 v[14:17], v[130:133], v[234:237], v[14:17]
	v_mfma_f32_16x16x32_bf16 v[10:13], v[160:163], v[234:237], v[10:13]
	v_mfma_f32_16x16x32_bf16 v[54:57], v[168:171], v[210:213], v[54:57]
	v_mfma_f32_16x16x32_bf16 v[50:53], v[202:205], v[210:213], v[50:53]
	v_mfma_f32_16x16x32_bf16 v[38:41], v[168:171], v[218:221], v[38:41]
	v_mfma_f32_16x16x32_bf16 v[34:37], v[202:205], v[218:221], v[34:37]
	v_mfma_f32_16x16x32_bf16 v[22:25], v[168:171], v[226:229], v[22:25]
	v_mfma_f32_16x16x32_bf16 v[18:21], v[202:205], v[226:229], v[18:21]
	v_mfma_f32_16x16x32_bf16 v[6:9], v[168:171], v[234:237], v[6:9]
	v_mfma_f32_16x16x32_bf16 v[2:5], v[202:205], v[234:237], v[2:5]
	v_mfma_f32_16x16x32_bf16 v[62:65], v[134:137], v[214:217], v[62:65]
	v_mfma_f32_16x16x32_bf16 v[58:61], v[164:167], v[214:217], v[58:61]
	v_mfma_f32_16x16x32_bf16 v[46:49], v[134:137], v[222:225], v[46:49]
	v_mfma_f32_16x16x32_bf16 v[42:45], v[164:167], v[222:225], v[42:45]
	v_mfma_f32_16x16x32_bf16 v[30:33], v[134:137], v[230:233], v[30:33]
	v_mfma_f32_16x16x32_bf16 v[26:29], v[164:167], v[230:233], v[26:29]
	v_mfma_f32_16x16x32_bf16 v[14:17], v[134:137], v[238:241], v[14:17]
	v_mfma_f32_16x16x32_bf16 v[10:13], v[164:167], v[238:241], v[10:13]
	v_mfma_f32_16x16x32_bf16 v[54:57], v[172:175], v[214:217], v[54:57]
	v_mfma_f32_16x16x32_bf16 v[50:53], v[206:209], v[214:217], v[50:53]
	v_mfma_f32_16x16x32_bf16 v[38:41], v[172:175], v[222:225], v[38:41]
	v_mfma_f32_16x16x32_bf16 v[34:37], v[206:209], v[222:225], v[34:37]
	v_mfma_f32_16x16x32_bf16 v[22:25], v[172:175], v[230:233], v[22:25]
	v_mfma_f32_16x16x32_bf16 v[18:21], v[206:209], v[230:233], v[18:21]
	v_mfma_f32_16x16x32_bf16 v[6:9], v[172:175], v[238:241], v[6:9]
	v_mfma_f32_16x16x32_bf16 v[2:5], v[206:209], v[238:241], v[2:5]
	s_barrier
	s_add_u32 s2, s2, 0x100
	s_addc_u32 s3, s3, 0
	s_add_u32 s20, s20, 0x100
	s_addc_u32 s21, s21, 0
	s_cmp_ge_u32 s22, s63
	s_mov_b32 s10, s22
	s_cbranch_scc0 .LBB0_294
	v_readlane_b32 s2, v255, 24
	v_readlane_b32 s3, v255, 25
	s_and_b64 vcc, exec, s[2:3]
	s_cbranch_vccz .LBB0_297
	s_barrier

.LBB0_300:
	s_andn2_b64 vcc, exec, s[2:3]
	s_cbranch_vccnz .LBB0_302
	s_cmpk_lt_i32 s16, 0x80
	s_movk_i32 s2, 0x3000
	s_cselect_b32 s2, 0x1800, s2
	s_cmp_gt_i32 s16, 63
	s_cselect_b32 s2, s2, 0
	s_lshl_b32 s2, s2, 2
	v_readlane_b32 s3, v255, 43
	v_lshl_or_b32 v130, s28, 8, v200
	s_add_u32 s2, s3, s2
	v_readlane_b32 s3, v255, 44
	v_ashrrev_i32_e32 v131, 31, v130
	s_addc_u32 s3, s3, 0
	v_lshlrev_b64 v[168:169], 2, v[130:131]
	v_lshl_add_u64 v[136:137], s[2:3], 0, v[168:169]
	global_load_dwordx4 v[132:135], v[136:137], off offset:16
	global_load_dwordx4 v[162:165], v[136:137], off
	global_load_dwordx4 v[172:175], v[136:137], off offset:528
	global_load_dwordx4 v[242:245], v[136:137], off offset:512
	v_mov_b32_e32 v143, v142
	v_readlane_b32 s2, v255, 26
	v_readlane_b32 s3, v255, 27
	v_ashrrev_i32_e32 v171, 31, v170
	s_waitcnt vmcnt(2)
	v_pk_mul_f32 v[130:131], v[142:143], v[134:135]
	v_pk_mul_f32 v[160:161], v[142:143], v[164:165]
	v_pk_mul_f32 v[132:133], v[154:155], v[132:133]
	v_pk_mul_f32 v[162:163], v[154:155], v[162:163]
	s_waitcnt vmcnt(0)
	v_pk_mul_f32 v[164:165], v[142:143], v[244:245]
	v_pk_mul_f32 v[166:167], v[154:155], v[242:243]
	v_pk_mul_f32 v[134:135], v[142:143], v[174:175]
	v_pk_mul_f32 v[136:137], v[154:155], v[172:173]
	v_lshl_add_u64 v[172:173], s[2:3], 0, v[168:169]
	v_lshlrev_b64 v[174:175], 12, v[170:171]
	v_lshl_add_u64 v[182:183], v[172:173], 0, v[174:175]
	global_load_dwordx4 v[202:205], v[182:183], off offset:16
	global_load_dwordx4 v[206:209], v[182:183], off
	global_load_dwordx4 v[210:213], v[182:183], off offset:528
	global_load_dwordx4 v[214:217], v[182:183], off offset:512
	v_or_b32_e32 v182, 16, v170
	v_ashrrev_i32_e32 v183, 31, v182
	v_lshlrev_b64 v[182:183], 12, v[182:183]
	v_lshl_add_u64 v[184:185], v[172:173], 0, v[182:183]
	global_load_dwordx4 v[218:221], v[184:185], off offset:16
	global_load_dwordx4 v[222:225], v[184:185], off
	global_load_dwordx4 v[226:229], v[184:185], off offset:528
	global_load_dwordx4 v[230:233], v[184:185], off offset:512
	v_lshl_add_u64 v[184:185], s[48:49], 0, v[174:175]
	v_lshl_add_u64 v[184:185], v[184:185], 0, v[168:169]
	v_lshl_add_u64 v[182:183], s[48:49], 0, v[182:183]
	v_lshl_add_u64 v[182:183], v[182:183], 0, v[168:169]
	s_mov_b64 s[2:3], 0x80000
	s_waitcnt vmcnt(7)
	v_pk_fma_f32 v[204:205], v[124:125], v[130:131], v[204:205]
	v_pk_fma_f32 v[202:203], v[122:123], v[132:133], v[202:203]
	global_store_dwordx4 v[184:185], v[202:205], off offset:16
	s_waitcnt vmcnt(7)
	v_pk_fma_f32 v[208:209], v[128:129], v[160:161], v[208:209]
	v_pk_fma_f32 v[206:207], v[126:127], v[162:163], v[206:207]
	s_waitcnt vmcnt(5)
	v_pk_fma_f32 v[204:205], v[120:121], v[164:165], v[216:217]
	v_pk_fma_f32 v[202:203], v[118:119], v[166:167], v[214:215]
	global_store_dwordx4 v[184:185], v[202:205], off offset:512
	global_store_dwordx4 v[184:185], v[206:209], off
	s_nop 0
	v_pk_fma_f32 v[204:205], v[116:117], v[134:135], v[212:213]
	v_pk_fma_f32 v[202:203], v[114:115], v[136:137], v[210:211]
	global_store_dwordx4 v[184:185], v[202:205], off offset:528
	s_waitcnt vmcnt(6)
	s_nop 0
	v_pk_fma_f32 v[204:205], v[112:113], v[160:161], v[224:225]
	v_pk_fma_f32 v[202:203], v[110:111], v[162:163], v[222:223]
	global_store_dwordx4 v[182:183], v[202:205], off
	s_nop 1
	v_pk_fma_f32 v[204:205], v[108:109], v[130:131], v[220:221]
	v_pk_fma_f32 v[202:203], v[106:107], v[132:133], v[218:219]
	global_store_dwordx4 v[182:183], v[202:205], off offset:16
	s_waitcnt vmcnt(6)
	s_nop 0
	v_pk_fma_f32 v[204:205], v[104:105], v[164:165], v[232:233]
	v_pk_fma_f32 v[202:203], v[102:103], v[166:167], v[230:231]
	global_store_dwordx4 v[182:183], v[202:205], off offset:512
	s_nop 1
	v_pk_fma_f32 v[204:205], v[100:101], v[134:135], v[228:229]
	v_pk_fma_f32 v[202:203], v[98:99], v[136:137], v[226:227]
	global_store_dwordx4 v[182:183], v[202:205], off offset:528
	v_or_b32_e32 v182, 32, v170
	v_ashrrev_i32_e32 v183, 31, v182
	v_lshlrev_b64 v[182:183], 12, v[182:183]
	v_lshl_add_u64 v[184:185], v[172:173], 0, v[182:183]
	global_load_dwordx4 v[202:205], v[184:185], off offset:16
	global_load_dwordx4 v[206:209], v[184:185], off
	global_load_dwordx4 v[210:213], v[184:185], off offset:528
	global_load_dwordx4 v[214:217], v[184:185], off offset:512
	v_or_b32_e32 v170, 48, v170
	v_ashrrev_i32_e32 v171, 31, v170
	v_lshlrev_b64 v[170:171], 12, v[170:171]
	v_lshl_add_u64 v[184:185], v[172:173], 0, v[170:171]
	global_load_dwordx4 v[218:221], v[184:185], off offset:16
	global_load_dwordx4 v[222:225], v[184:185], off
	global_load_dwordx4 v[226:229], v[184:185], off offset:528
	global_load_dwordx4 v[230:233], v[184:185], off offset:512
	v_lshl_add_u64 v[182:183], s[48:49], 0, v[182:183]
	v_lshl_add_u64 v[182:183], v[182:183], 0, v[168:169]
	v_lshl_add_u64 v[170:171], s[48:49], 0, v[170:171]
	v_lshl_add_u64 v[170:171], v[170:171], 0, v[168:169]
	s_waitcnt vmcnt(7)
	v_pk_fma_f32 v[204:205], v[92:93], v[130:131], v[204:205]
	v_pk_fma_f32 v[202:203], v[90:91], v[132:133], v[202:203]
	global_store_dwordx4 v[182:183], v[202:205], off offset:16
	s_waitcnt vmcnt(7)
	v_pk_fma_f32 v[208:209], v[96:97], v[160:161], v[208:209]
	v_pk_fma_f32 v[206:207], v[94:95], v[162:163], v[206:207]
	s_waitcnt vmcnt(5)
	v_pk_fma_f32 v[204:205], v[88:89], v[164:165], v[216:217]
	v_pk_fma_f32 v[202:203], v[86:87], v[166:167], v[214:215]
	global_store_dwordx4 v[182:183], v[202:205], off offset:512
	global_store_dwordx4 v[182:183], v[206:209], off
	s_nop 0
	v_pk_fma_f32 v[204:205], v[84:85], v[134:135], v[212:213]
	v_pk_fma_f32 v[202:203], v[82:83], v[136:137], v[210:211]
	global_store_dwordx4 v[182:183], v[202:205], off offset:528
	s_waitcnt vmcnt(6)
	s_nop 0
	v_pk_fma_f32 v[204:205], v[80:81], v[160:161], v[224:225]
	v_pk_fma_f32 v[202:203], v[78:79], v[162:163], v[222:223]
	global_store_dwordx4 v[170:171], v[202:205], off
	s_nop 1
	v_pk_fma_f32 v[204:205], v[76:77], v[130:131], v[220:221]
	v_pk_fma_f32 v[202:203], v[74:75], v[132:133], v[218:219]
	global_store_dwordx4 v[170:171], v[202:205], off offset:16
	s_waitcnt vmcnt(6)
	s_nop 0
	v_pk_fma_f32 v[204:205], v[72:73], v[164:165], v[232:233]
	v_pk_fma_f32 v[202:203], v[70:71], v[166:167], v[230:231]
	global_store_dwordx4 v[170:171], v[202:205], off offset:512
	s_nop 1
	v_pk_fma_f32 v[204:205], v[68:69], v[134:135], v[228:229]
	v_pk_fma_f32 v[202:203], v[66:67], v[136:137], v[226:227]
	global_store_dwordx4 v[170:171], v[202:205], off offset:528
	v_lshl_add_u64 v[170:171], v[174:175], 0, s[2:3]
	v_lshl_add_u64 v[182:183], v[172:173], 0, v[170:171]
	global_load_dwordx4 v[202:205], v[182:183], off offset:16
	global_load_dwordx4 v[206:209], v[182:183], off
	global_load_dwordx4 v[210:213], v[182:183], off offset:528
	global_load_dwordx4 v[214:217], v[182:183], off offset:512
	s_mov_b64 s[2:3], 0x90000
	v_lshl_add_u64 v[182:183], v[174:175], 0, s[2:3]
	v_lshl_add_u64 v[184:185], v[172:173], 0, v[182:183]
	global_load_dwordx4 v[218:221], v[184:185], off offset:16
	global_load_dwordx4 v[222:225], v[184:185], off
	global_load_dwordx4 v[226:229], v[184:185], off offset:528
	global_load_dwordx4 v[230:233], v[184:185], off offset:512
	v_lshl_add_u64 v[170:171], s[48:49], 0, v[170:171]
	v_lshl_add_u64 v[170:171], v[170:171], 0, v[168:169]
	s_mov_b64 s[2:3], 0xa0000
	s_waitcnt vmcnt(7)
	v_pk_fma_f32 v[204:205], v[60:61], v[130:131], v[204:205]
	v_pk_fma_f32 v[202:203], v[58:59], v[132:133], v[202:203]
	global_store_dwordx4 v[170:171], v[202:205], off offset:16
	s_waitcnt vmcnt(7)
	v_pk_fma_f32 v[208:209], v[64:65], v[160:161], v[208:209]
	v_pk_fma_f32 v[206:207], v[62:63], v[162:163], v[206:207]
	s_waitcnt vmcnt(5)
	v_pk_fma_f32 v[204:205], v[56:57], v[164:165], v[216:217]
	v_pk_fma_f32 v[202:203], v[54:55], v[166:167], v[214:215]
	global_store_dwordx4 v[170:171], v[202:205], off offset:512
	global_store_dwordx4 v[170:171], v[206:209], off
	s_nop 0
	v_pk_fma_f32 v[204:205], v[52:53], v[134:135], v[212:213]
	v_pk_fma_f32 v[202:203], v[50:51], v[136:137], v[210:211]
	global_store_dwordx4 v[170:171], v[202:205], off offset:528
	v_lshl_add_u64 v[170:171], s[48:49], 0, v[182:183]
	v_lshl_add_u64 v[170:171], v[170:171], 0, v[168:169]
	s_waitcnt vmcnt(6)
	v_pk_fma_f32 v[204:205], v[48:49], v[160:161], v[224:225]
	v_pk_fma_f32 v[202:203], v[46:47], v[162:163], v[222:223]
	global_store_dwordx4 v[170:171], v[202:205], off
	v_lshl_add_u64 v[182:183], v[174:175], 0, s[2:3]
	s_mov_b64 s[2:3], 0xb0000
	v_pk_fma_f32 v[204:205], v[44:45], v[130:131], v[220:221]
	v_pk_fma_f32 v[202:203], v[42:43], v[132:133], v[218:219]
	global_store_dwordx4 v[170:171], v[202:205], off offset:16
	v_lshl_add_u64 v[174:175], v[174:175], 0, s[2:3]
	v_lshl_add_u64 v[184:185], v[172:173], 0, v[174:175]
	s_waitcnt vmcnt(6)
	v_pk_fma_f32 v[204:205], v[40:41], v[164:165], v[232:233]
	v_pk_fma_f32 v[202:203], v[38:39], v[166:167], v[230:231]
	global_store_dwordx4 v[170:171], v[202:205], off offset:512
	v_lshl_add_u64 v[174:175], s[48:49], 0, v[174:175]
	s_nop 0
	v_pk_fma_f32 v[204:205], v[36:37], v[134:135], v[228:229]
	v_pk_fma_f32 v[202:203], v[34:35], v[136:137], v[226:227]
	global_store_dwordx4 v[170:171], v[202:205], off offset:528
	v_lshl_add_u64 v[170:171], v[172:173], 0, v[182:183]
	global_load_dwordx4 v[202:205], v[170:171], off offset:16
	global_load_dwordx4 v[206:209], v[170:171], off
	global_load_dwordx4 v[210:213], v[170:171], off offset:528
	global_load_dwordx4 v[214:217], v[170:171], off offset:512
	s_nop 0
	global_load_dwordx4 v[170:173], v[184:185], off offset:16
	global_load_dwordx4 v[218:221], v[184:185], off
	global_load_dwordx4 v[222:225], v[184:185], off offset:528
	global_load_dwordx4 v[226:229], v[184:185], off offset:512
	v_lshl_add_u64 v[182:183], s[48:49], 0, v[182:183]
	v_lshl_add_u64 v[182:183], v[182:183], 0, v[168:169]
	v_lshl_add_u64 v[168:169], v[174:175], 0, v[168:169]
	s_waitcnt vmcnt(7)
	v_pk_fma_f32 v[204:205], v[28:29], v[130:131], v[204:205]
	v_pk_fma_f32 v[202:203], v[26:27], v[132:133], v[202:203]
	global_store_dwordx4 v[182:183], v[202:205], off offset:16
	s_waitcnt vmcnt(7)
	v_pk_fma_f32 v[208:209], v[32:33], v[160:161], v[208:209]
	v_pk_fma_f32 v[206:207], v[30:31], v[162:163], v[206:207]
	s_waitcnt vmcnt(5)
	v_pk_fma_f32 v[204:205], v[24:25], v[164:165], v[216:217]
	v_pk_fma_f32 v[202:203], v[22:23], v[166:167], v[214:215]
	global_store_dwordx4 v[182:183], v[202:205], off offset:512
	global_store_dwordx4 v[182:183], v[206:209], off
	s_nop 0
	v_pk_fma_f32 v[204:205], v[20:21], v[134:135], v[212:213]
	v_pk_fma_f32 v[202:203], v[18:19], v[136:137], v[210:211]
	global_store_dwordx4 v[182:183], v[202:205], off offset:528
	s_waitcnt vmcnt(6)
	s_nop 0
	v_pk_fma_f32 v[204:205], v[16:17], v[160:161], v[220:221]
	v_pk_fma_f32 v[202:203], v[14:15], v[162:163], v[218:219]
	v_pk_fma_f32 v[162:163], v[12:13], v[130:131], v[172:173]
	v_pk_fma_f32 v[160:161], v[10:11], v[132:133], v[170:171]
	s_waitcnt vmcnt(4)
	v_pk_fma_f32 v[132:133], v[8:9], v[164:165], v[228:229]
	v_pk_fma_f32 v[130:131], v[6:7], v[166:167], v[226:227]
	global_store_dwordx4 v[168:169], v[130:133], off offset:512
	global_store_dwordx4 v[168:169], v[202:205], off
	global_store_dwordx4 v[168:169], v[160:163], off offset:16
	v_pk_fma_f32 v[132:133], v[4:5], v[134:135], v[224:225]
	v_pk_fma_f32 v[130:131], v[2:3], v[136:137], v[222:223]
	global_store_dwordx4 v[168:169], v[130:133], off offset:528
